# attn loop: p0 exps moved under the next tile's QK MFMAs (peeled first iteration) to balance VALU per MFMA between QK and PV phases
# speedup vs baseline: 1.0098x; 1.0098x over previous
; #define SBAR() __builtin_amdgcn_sched_barrier(0)
; __device__ __forceinline__ void finishSM(f32x16& p0, f32x16& p1, float alpha, float& l_reg, bf16x8& pa0, bf16x8& pa1, bf16x8& pa2, bf16x8& pa3) {
; #pragma unroll
;   for (int r = 0; r < 16; ++r) p1[r] = __builtin_amdgcn_exp2f(p1[r]);
;   float ps = 0;
; #pragma unroll
;   for (int r = 0; r < 16; ++r) ps += p0[r];
; #pragma unroll
;   for (int r = 0; r < 16; ++r) ps += p1[r];
;   { auto rr = __builtin_amdgcn_permlane32_swap(__float_as_uint(ps), __float_as_uint(ps), false, false);
;     ps = __uint_as_float(rr[0]) + __uint_as_float(rr[1]); }
;   l_reg = l_reg * alpha + ps;
;     ...
;   PK4(p0, 0, pa0); PK4(p0, 8, pa1); PK4(p1, 0, pa2); PK4(p1, 8, pa3);
;     ...
; }
; __device__ __forceinline__ void qkt(f32x16& p0, f32x16& p1, const char* Ks, const bf16x8* qr, const char* qrl, int r32, int hi) {
;   p0 = f32x16{}; p1 = f32x16{};
; #pragma unroll
;   for (int d0 = 0; d0 < 8; ++d0) { int cb = (d0 * 16 + hi * 8) * 2;
;     bf16x8 b0 = *reinterpret_cast<const bf16x8*>(Ks + KSWZ(r32, cb));
;     bf16x8 b1 = *reinterpret_cast<const bf16x8*>(Ks + KSWZ(32 + r32, cb));
;     p0 = __builtin_amdgcn_mfma_f32_32x32x16_bf16(b0, qr[d0], p0, 0, 0, 0);
;     p1 = __builtin_amdgcn_mfma_f32_32x32x16_bf16(b1, qr[d0], p1, 0, 0, 0); }
; #pragma unroll
;   for (int d0 = 8; d0 < 12; ++d0) { int cb = (d0 * 16 + hi * 8) * 2;
;     bf16x8 b0 = *reinterpret_cast<const bf16x8*>(Ks + KSWZ(r32, cb));
;     bf16x8 b1 = *reinterpret_cast<const bf16x8*>(Ks + KSWZ(32 + r32, cb));
;     bf16x8 qf = *reinterpret_cast<const bf16x8*>(qrl + (((2 * (d0 - 8) + hi) ^ ((r32 >> 1) & 7)) << 4));
;     p0 = __builtin_amdgcn_mfma_f32_32x32x16_bf16(b0, qf, p0, 0, 0, 0);
;     p1 = __builtin_amdgcn_mfma_f32_32x32x16_bf16(b1, qf, p1, 0, 0, 0); }
; }
; __device__ __forceinline__ void attn_unit(const bf16_t* __restrict__ Qb, const bf16_t* __restrict__ Kn, const bf16_t* __restrict__ Vh, const bf16_t* __restrict__ Kr,
;                                           bf16_t* GO, int seq, char* lds, const int tid) {
;     ...
;     SWRITE(bn, 0); SLOAD(0, (j + 2) * KVBLK); SBAR();
.LBB0_1151:
	s_sub_i32 s30, s76, 1
	s_cmp_eq_u32 s76, 0
	s_cselect_b32 s30, 2, s30
	s_add_i32 s18, s76, 1
	s_cmp_lg_u32 s76, 2
	s_cselect_b32 s18, s18, 0
	ds_read_b128 v[64:67], v199 offset:36864
	ds_read_b128 v[68:71], v199 offset:49152
	ds_read_b128 v[232:235], v205 offset:36864
	ds_read_b128 v[236:239], v205 offset:49152
	ds_read_b128 v[240:243], v206 offset:36864
	ds_read_b128 v[248:251], v206 offset:49152
	v_exp_f32_e32 v162, v162
	v_add_f32_e32 v211, v225, v228
	v_exp_f32_e32 v163, v163
	v_add_f32_e32 v211, v226, v211
	v_exp_f32_e32 v160, v160
	s_waitcnt lgkmcnt(4)
	v_mfma_f32_32x32x16_bf16 v[80:95], v[64:67], v[124:127], 0
	v_add_f32_e32 v211, v229, v211
	v_exp_f32_e32 v161, v161
	v_add_f32_e32 v211, v227, v211
	v_exp_f32_e32 v158, v158
	v_mfma_f32_32x32x16_bf16 v[64:79], v[68:71], v[124:127], 0
	v_add_f32_e32 v211, v230, v211
	v_exp_f32_e32 v159, v159
	v_add_f32_e32 v211, v223, v211
	v_exp_f32_e32 v156, v156
	s_waitcnt lgkmcnt(2)
	v_mfma_f32_32x32x16_bf16 v[80:95], v[232:235], v[120:123], v[80:95]
	ds_read_b128 v[232:235], v208 offset:36864
	v_add_f32_e32 v211, v224, v211
	v_exp_f32_e32 v157, v157
	v_add_f32_e32 v211, v219, v211
	v_exp_f32_e32 v154, v154
	v_mfma_f32_32x32x16_bf16 v[64:79], v[236:239], v[120:123], v[64:79]
	ds_read_b128 v[236:239], v208 offset:49152
	v_add_f32_e32 v211, v221, v211
	v_exp_f32_e32 v155, v155
	v_add_f32_e32 v211, v220, v211
	v_exp_f32_e32 v152, v152
	s_waitcnt lgkmcnt(2)
	v_mfma_f32_32x32x16_bf16 v[80:95], v[240:243], v[116:119], v[80:95]
	ds_read_b128 v[240:243], v207 offset:36864
	v_add_f32_e32 v211, v222, v211
	v_exp_f32_e32 v153, v153
	v_add_f32_e32 v211, v215, v211
	v_exp_f32_e32 v150, v150
	v_mfma_f32_32x32x16_bf16 v[64:79], v[248:251], v[116:119], v[64:79]
	ds_read_b128 v[248:251], v207 offset:49152
	v_add_f32_e32 v211, v217, v211
	v_exp_f32_e32 v151, v151
	v_add_f32_e32 v211, v216, v211
	v_exp_f32_e32 v148, v148
	s_waitcnt lgkmcnt(2)
	v_mfma_f32_32x32x16_bf16 v[80:95], v[232:235], v[112:115], v[80:95]
	ds_read_b128 v[232:235], v204 offset:36864
	v_add_f32_e32 v211, v218, v211
	v_exp_f32_e32 v149, v149
	v_add_f32_e32 v212, v162, v163
	v_add_f32_e32 v212, v160, v212
	v_add_f32_e32 v212, v161, v212
	v_mfma_f32_32x32x16_bf16 v[64:79], v[236:239], v[112:115], v[64:79]
	ds_read_b128 v[236:239], v204 offset:49152
	v_add_f32_e32 v212, v158, v212
	v_add_f32_e32 v212, v159, v212
	v_add_f32_e32 v212, v156, v212
	v_add_f32_e32 v212, v157, v212
	v_add_f32_e32 v212, v154, v212
	v_add_f32_e32 v212, v155, v212
	s_waitcnt lgkmcnt(2)
	v_mfma_f32_32x32x16_bf16 v[80:95], v[240:243], v[108:111], v[80:95]
	ds_read_b128 v[240:243], v203 offset:36864
	v_add_f32_e32 v212, v152, v212
	v_add_f32_e32 v212, v153, v212
	v_add_f32_e32 v212, v150, v212
	v_add_f32_e32 v212, v151, v212
	v_add_f32_e32 v212, v148, v212
	v_add_f32_e32 v212, v149, v212
	v_mfma_f32_32x32x16_bf16 v[64:79], v[248:251], v[108:111], v[64:79]
	ds_read_b128 v[248:251], v203 offset:49152
	v_add_f32_e32 v211, v211, v212
	v_mov_b32_e32 v212, v211
	s_lshl_b32 s19, s18, 14
	v_add_u32_e32 v231, s19, v183
	s_waitcnt vmcnt(0)
	ds_write_b128 v231, v[140:143]
	v_add_u32_e32 v140, s19, v184
	ds_write_b128 v140, v[144:147]
	ds_write_b128 v185, v[136:139] offset:12288
	s_waitcnt lgkmcnt(5)
	v_mfma_f32_32x32x16_bf16 v[80:95], v[232:235], v[104:107], v[80:95]
	ds_read_b128 v[232:235], v200 offset:36864
	ds_write_b128 v185, v[132:135] offset:24576
	s_mov_b32 s18, 0xfffa0000
	ds_write_b128 v186, v[128:131] offset:12288
	v_add_co_u32_e32 v128, vcc, s18, v168
	s_mov_b32 s18, 0xfffc0000
	s_nop 0
	v_addc_co_u32_e32 v129, vcc, -1, v169, vcc
	v_add_co_u32_e32 v130, vcc, s18, v168
	s_movk_i32 s18, 0xe000
	s_nop 0
	v_addc_co_u32_e32 v131, vcc, -1, v169, vcc
	v_mfma_f32_32x32x16_bf16 v[64:79], v[236:239], v[104:107], v[64:79]
	ds_read_b128 v[236:239], v200 offset:49152
	global_load_dwordx4 v[140:143], v[128:129], off
	global_load_dwordx4 v[136:139], v[128:129], off offset:-256
	global_load_dwordx4 v[144:147], v[130:131], off
	global_load_dwordx4 v[132:135], v[130:131], off offset:-256
	v_add_co_u32_e32 v128, vcc, s18, v166
	s_nop 1
	v_addc_co_u32_e32 v129, vcc, -1, v167, vcc
	s_waitcnt lgkmcnt(7)
; __device__ __forceinline__ void partialSM(f32x16& p0, f32x16& p1, float& m_reg, float& mn, float& alpha) {
;   constexpr float C = SCALE * 1.4426950408889634f;
;   float pmax = p0[0];
; #pragma unroll
;   for (int r = 1; r < 16; ++r) pmax = fmaxf(pmax, p0[r]);
; #pragma unroll
;   for (int r = 0; r < 16; ++r) pmax = fmaxf(pmax, p1[r]);
;   { auto rr = __builtin_amdgcn_permlane32_swap(__float_as_uint(pmax), __float_as_uint(pmax), false, false);
;     pmax = fmaxf(__uint_as_float(rr[0]), __uint_as_float(rr[1])); }
;   if (__builtin_expect(__all(pmax - m_reg <= THR / SCALE), 1)) { mn = m_reg; alpha = 1.f; }
;   else { mn = fmaxf(m_reg, pmax); alpha = __builtin_amdgcn_exp2f((m_reg - mn) * C); m_reg = mn; }
;   float mnC = -mn * C;
; #pragma unroll
;   for (int r = 0; r < 16; ++r) p0[r] = fmaf(p0[r], C, mnC);
; #pragma unroll
;   for (int r = 0; r < 16; ++r) p1[r] = fmaf(p1[r], C, mnC);
; #pragma unroll
;   for (int r = 0; r < 16; ++r) p0[r] = __builtin_amdgcn_exp2f(p0[r]);
; }
; __device__ __forceinline__ void finishSM(f32x16& p0, f32x16& p1, float alpha, float& l_reg, bf16x8& pa0, bf16x8& pa1, bf16x8& pa2, bf16x8& pa3) {
; #pragma unroll
;   for (int r = 0; r < 16; ++r) p1[r] = __builtin_amdgcn_exp2f(p1[r]);
;   float ps = 0;
; #pragma unroll
;   for (int r = 0; r < 16; ++r) ps += p0[r];
; #pragma unroll
;   for (int r = 0; r < 16; ++r) ps += p1[r];
;   { auto rr = __builtin_amdgcn_permlane32_swap(__float_as_uint(ps), __float_as_uint(ps), false, false);
;     ps = __uint_as_float(rr[0]) + __uint_as_float(rr[1]); }
;   l_reg = l_reg * alpha + ps;
;     ...
;   PK4(p0, 0, pa0); PK4(p0, 8, pa1); PK4(p1, 0, pa2); PK4(p1, 8, pa3);
;     ...
; }
	v_mfma_f32_32x32x16_bf16 v[80:95], v[240:243], v[100:103], v[80:95]
	ds_read_b128 v[240:243], v191 offset:36864
	global_load_dwordx4 v[128:131], v[128:129], off
	v_cvt_pk_bf16_f32 v158, v158, v159
	v_cvt_pk_bf16_f32 v159, v156, v157
	v_permlane32_swap_b32_e32 v211, v212
	v_cvt_pk_bf16_f32 v156, v162, v163
	v_cvt_pk_bf16_f32 v157, v160, v161
	v_mfma_f32_32x32x16_bf16 v[64:79], v[248:251], v[100:103], v[64:79]
	ds_read_b128 v[248:251], v202 offset:49152
	v_cvt_pk_bf16_f32 v160, v154, v155
	v_cvt_pk_bf16_f32 v161, v152, v153
	v_cvt_pk_bf16_f32 v162, v150, v151
	v_cvt_pk_bf16_f32 v163, v148, v149
	v_add_f32_e32 v211, v211, v212
	v_cvt_pk_bf16_f32 v148, v225, v228
	s_waitcnt lgkmcnt(2)
	v_mfma_f32_32x32x16_bf16 v[80:95], v[232:235], v[96:99], v[80:95]
	ds_read_b128 v[232:235], v182
	v_cvt_pk_bf16_f32 v149, v226, v229
	v_cvt_pk_bf16_f32 v150, v227, v230
	v_cvt_pk_bf16_f32 v151, v223, v224
	v_cvt_pk_bf16_f32 v152, v219, v221
	v_cvt_pk_bf16_f32 v153, v220, v222
	v_cvt_pk_bf16_f32 v154, v215, v217
	v_mfma_f32_32x32x16_bf16 v[64:79], v[236:239], v[96:99], v[64:79]
	ds_read_b128 v[236:239], v198 offset:36864
	v_cvt_pk_bf16_f32 v155, v216, v218
	v_fma_f32 v176, v209, v176, v211
	s_waitcnt lgkmcnt(1)
	v_mfma_f32_32x32x16_bf16 v[80:95], v[240:243], v[232:235], v[80:95]
	ds_read_b128 v[240:243], v201 offset:49152
	v_mfma_f32_32x32x16_bf16 v[64:79], v[248:251], v[232:235], v[64:79]
	ds_read_b128 v[248:251], v181
	ds_read_b128 v[232:235], v187 offset:36864
	s_waitcnt lgkmcnt(1)
	v_mfma_f32_32x32x16_bf16 v[80:95], v[236:239], v[248:251], v[80:95]
	ds_read_b128 v[236:239], v189 offset:49152
	v_mfma_f32_32x32x16_bf16 v[64:79], v[240:243], v[248:251], v[64:79]
	ds_read_b128 v[240:243], v179
	ds_read_b128 v[248:251], v188 offset:36864
	s_waitcnt lgkmcnt(1)
	v_mfma_f32_32x32x16_bf16 v[80:95], v[232:235], v[240:243], v[80:95]
	ds_read_b128 v[232:235], v190 offset:49152
	v_mfma_f32_32x32x16_bf16 v[64:79], v[236:239], v[240:243], v[64:79]
	ds_read_b128 v[236:239], v177
	s_waitcnt lgkmcnt(0)
	v_mfma_f32_32x32x16_bf16 v[80:95], v[248:251], v[236:239], v[80:95]
	v_mfma_f32_32x32x16_bf16 v[64:79], v[232:235], v[236:239], v[64:79]
	s_lshl_b32 s31, s30, 14
	v_add_u32_e32 v180, s31, v178
	ds_read_b64_tr_b16 v[240:241], v180 offset:0
	ds_read_b64_tr_b16 v[242:243], v180 offset:2048
	ds_read_b64_tr_b16 v[248:249], v180 offset:512
	ds_read_b64_tr_b16 v[250:251], v180 offset:2560
	ds_read_b64_tr_b16 v[232:233], v180 offset:1024
	ds_read_b64_tr_b16 v[234:235], v180 offset:3072
	ds_read_b64_tr_b16 v[236:237], v180 offset:1536
	ds_read_b64_tr_b16 v[238:239], v180 offset:3584
	s_nop 3
	v_max3_f32 v194, v80, v81, v82
	v_max3_f32 v195, v64, v65, v66
	v_max3_f32 v194, v194, v83, v84
	v_max3_f32 v195, v195, v67, v68
	s_waitcnt lgkmcnt(4)
	v_mfma_f32_32x32x16_bf16 v[32:47], v[148:151], v[240:243], v[32:47]
	ds_read_b64_tr_b16 v[240:241], v180 offset:4096
	ds_read_b64_tr_b16 v[242:243], v180 offset:6144
	v_max3_f32 v194, v194, v85, v86
	v_max3_f32 v195, v195, v69, v70
	v_max3_f32 v194, v194, v87, v88
	v_max3_f32 v195, v195, v71, v72
	v_mfma_f32_32x32x16_bf16 v[48:63], v[148:151], v[248:251], v[48:63]
	ds_read_b64_tr_b16 v[248:249], v180 offset:4608
	ds_read_b64_tr_b16 v[250:251], v180 offset:6656
	v_max3_f32 v194, v194, v89, v90
	v_max3_f32 v195, v195, v73, v74
	v_max3_f32 v194, v194, v91, v92
	v_max3_f32 v195, v195, v75, v76
	s_waitcnt lgkmcnt(4)
	v_mfma_f32_32x32x16_bf16 v[16:31], v[148:151], v[232:235], v[16:31]
	ds_read_b64_tr_b16 v[232:233], v180 offset:5120
	ds_read_b64_tr_b16 v[234:235], v180 offset:7168
	v_max3_f32 v194, v194, v93, v94
	v_max3_f32 v195, v195, v77, v78
	v_max3_f32 v194, v194, v95, v195
	v_max_f32_e32 v194, v194, v79
	v_mfma_f32_32x32x16_bf16 v[0:15], v[148:151], v[236:239], v[0:15]
	ds_read_b64_tr_b16 v[236:237], v180 offset:5632
	ds_read_b64_tr_b16 v[238:239], v180 offset:7680
	v_mov_b32_e32 v195, v194
	s_nop 1
	v_permlane32_swap_b32_e32 v194, v195
	v_max_f32_e32 v194, v194, v195
	s_waitcnt lgkmcnt(4)
	v_mfma_f32_32x32x16_bf16 v[32:47], v[152:155], v[240:243], v[32:47]
	ds_read_b64_tr_b16 v[240:241], v180 offset:8192
	ds_read_b64_tr_b16 v[242:243], v180 offset:10240
	v_sub_f32_e32 v195, v194, v210
	v_cmp_ge_f32_e32 vcc, s15, v195
	v_mfma_f32_32x32x16_bf16 v[48:63], v[152:155], v[248:251], v[48:63]
	ds_read_b64_tr_b16 v[248:249], v180 offset:8704
	ds_read_b64_tr_b16 v[250:251], v180 offset:10752
	s_cmp_eq_u64 vcc, exec
	s_cselect_b64 s[40:41], -1, 0
	s_cbranch_scc1 .Lattn_fast1p
	v_max_f32_e32 v194, v210, v194
	v_sub_f32_e32 v195, v210, v194
	v_mul_f32_e32 v195, 0x3dd53b94, v195
	v_exp_f32_e32 v214, v195
	v_mov_b32_e32 v210, v194
	s_branch .Lattn_join1p

; #define SBAR() __builtin_amdgcn_sched_barrier(0)
; __device__ __forceinline__ void partialSM(f32x16& p0, f32x16& p1, float& m_reg, float& mn, float& alpha) {
;     ...
;   float mnC = -mn * C;
; #pragma unroll
;   for (int r = 0; r < 16; ++r) p0[r] = fmaf(p0[r], C, mnC);
; #pragma unroll
;   for (int r = 0; r < 16; ++r) p1[r] = fmaf(p1[r], C, mnC);
; #pragma unroll
;   for (int r = 0; r < 16; ++r) p0[r] = __builtin_amdgcn_exp2f(p0[r]);
; template <int D0> __device__ __forceinline__ void pv_one(f32x16& od, int vb, bf16x8 pa0, bf16x8 pa1, bf16x8 pa2, bf16x8 pa3) {
;   const s16x4 l0 = tr_read<v_rd_off(D0, 0, 0)>(vb), h0 = tr_read<v_rd_off(D0, 0, 1)>(vb), l1 = tr_read<v_rd_off(D0, 1, 0)>(vb), h1 = tr_read<v_rd_off(D0, 1, 1)>(vb);
;   const s16x4 l2 = tr_read<v_rd_off(D0, 2, 0)>(vb), h2 = tr_read<v_rd_off(D0, 2, 1)>(vb), l3 = tr_read<v_rd_off(D0, 3, 0)>(vb), h3 = tr_read<v_rd_off(D0, 3, 1)>(vb);
;   asm volatile("s_waitcnt lgkmcnt(0)" ::: "memory"); SBAR();
;     ...
;   od = __builtin_amdgcn_mfma_f32_32x32x16_bf16(pa0, PK(l0, h0), od, 0, 0, 0);
;   od = __builtin_amdgcn_mfma_f32_32x32x16_bf16(pa1, PK(l1, h1), od, 0, 0, 0);
;   od = __builtin_amdgcn_mfma_f32_32x32x16_bf16(pa2, PK(l2, h2), od, 0, 0, 0);
;   od = __builtin_amdgcn_mfma_f32_32x32x16_bf16(pa3, PK(l3, h3), od, 0, 0, 0);
;     ...
; }
; __device__ __forceinline__ void pv_d0(f32x16* o, int vb, bf16x8 pa0, bf16x8 pa1, bf16x8 pa2, bf16x8 pa3) {
;   pv_one<0>(o[0], vb, pa0, pa1, pa2, pa3); pv_one<1>(o[1], vb, pa0, pa1, pa2, pa3); pv_one<2>(o[2], vb, pa0, pa1, pa2, pa3); pv_one<3>(o[3], vb, pa0, pa1, pa2, pa3);
.Lattn_join1p:
	v_mul_f32_e32 v194, 0xbdd53b94, v210
	s_waitcnt lgkmcnt(4)
	v_mfma_f32_32x32x16_bf16 v[16:31], v[152:155], v[232:235], v[16:31]
	ds_read_b64_tr_b16 v[232:233], v180 offset:9216
	ds_read_b64_tr_b16 v[234:235], v180 offset:11264
	v_fmamk_f32 v225, v80, 0x3dd53b94, v194
	v_fmamk_f32 v228, v81, 0x3dd53b94, v194
	v_fmamk_f32 v226, v82, 0x3dd53b94, v194
	v_fmamk_f32 v229, v83, 0x3dd53b94, v194
	v_mfma_f32_32x32x16_bf16 v[0:15], v[152:155], v[236:239], v[0:15]
	ds_read_b64_tr_b16 v[236:237], v180 offset:9728
	ds_read_b64_tr_b16 v[238:239], v180 offset:11776
	v_fmamk_f32 v150, v76, 0x3dd53b94, v194
	v_fmamk_f32 v151, v77, 0x3dd53b94, v194
	v_fmamk_f32 v148, v78, 0x3dd53b94, v194
	v_fmamk_f32 v149, v79, 0x3dd53b94, v194
	s_waitcnt lgkmcnt(4)
	v_mfma_f32_32x32x16_bf16 v[32:47], v[156:159], v[240:243], v[32:47]
	ds_read_b64_tr_b16 v[240:241], v180 offset:12288
	ds_read_b64_tr_b16 v[242:243], v180 offset:14336
	v_fmamk_f32 v227, v84, 0x3dd53b94, v194
	v_fmamk_f32 v230, v85, 0x3dd53b94, v194
	v_fmamk_f32 v223, v86, 0x3dd53b94, v194
	v_fmamk_f32 v224, v87, 0x3dd53b94, v194
	v_mfma_f32_32x32x16_bf16 v[48:63], v[156:159], v[248:251], v[48:63]
	ds_read_b64_tr_b16 v[248:249], v180 offset:12800
	ds_read_b64_tr_b16 v[250:251], v180 offset:14848
	v_fmamk_f32 v154, v72, 0x3dd53b94, v194
	v_fmamk_f32 v155, v73, 0x3dd53b94, v194
	v_fmamk_f32 v152, v74, 0x3dd53b94, v194
	v_fmamk_f32 v153, v75, 0x3dd53b94, v194
	s_waitcnt lgkmcnt(4)
	v_mfma_f32_32x32x16_bf16 v[16:31], v[156:159], v[232:235], v[16:31]
	ds_read_b64_tr_b16 v[232:233], v180 offset:13312
	ds_read_b64_tr_b16 v[234:235], v180 offset:15360
	v_fmamk_f32 v219, v88, 0x3dd53b94, v194
	v_fmamk_f32 v221, v89, 0x3dd53b94, v194
	v_fmamk_f32 v220, v90, 0x3dd53b94, v194
	v_fmamk_f32 v222, v91, 0x3dd53b94, v194
	v_mfma_f32_32x32x16_bf16 v[0:15], v[156:159], v[236:239], v[0:15]
	ds_read_b64_tr_b16 v[236:237], v180 offset:13824
	ds_read_b64_tr_b16 v[238:239], v180 offset:15872
	v_fmamk_f32 v158, v68, 0x3dd53b94, v194
	v_fmamk_f32 v159, v69, 0x3dd53b94, v194
	v_fmamk_f32 v156, v70, 0x3dd53b94, v194
	v_fmamk_f32 v157, v71, 0x3dd53b94, v194
	s_waitcnt lgkmcnt(4)
	v_mfma_f32_32x32x16_bf16 v[32:47], v[160:163], v[240:243], v[32:47]
	v_fmamk_f32 v215, v92, 0x3dd53b94, v194
	v_fmamk_f32 v217, v93, 0x3dd53b94, v194
	v_fmamk_f32 v216, v94, 0x3dd53b94, v194
	v_fmamk_f32 v218, v95, 0x3dd53b94, v194
	v_mfma_f32_32x32x16_bf16 v[48:63], v[160:163], v[248:251], v[48:63]
	s_waitcnt lgkmcnt(0)
	v_mfma_f32_32x32x16_bf16 v[16:31], v[160:163], v[232:235], v[16:31]
	v_mfma_f32_32x32x16_bf16 v[0:15], v[160:163], v[236:239], v[0:15]
	v_fmamk_f32 v162, v64, 0x3dd53b94, v194
	v_fmamk_f32 v163, v65, 0x3dd53b94, v194
	v_fmamk_f32 v160, v66, 0x3dd53b94, v194
	v_fmamk_f32 v161, v67, 0x3dd53b94, v194
	s_and_b64 vcc, exec, s[40:41]
	s_cbranch_vccnz .Lattn_skip_rs1p
	s_and_saveexec_b64 s[18:19], s[38:39]
	ds_write_b32 v175, v214 offset:128
	s_or_b64 exec, exec, s[18:19]
	s_waitcnt lgkmcnt(0)
	v_add_u32_e32 v194, v173, v164
	ds_read_b128 v[232:235], v194 offset:224
	ds_read_b128 v[236:239], v194 offset:192
	ds_read_b128 v[240:243], v194 offset:160
	ds_read_b128 v[248:251], v194 offset:128
	s_waitcnt lgkmcnt(0)
	v_pk_mul_f32 v[44:45], v[44:45], v[232:233]
	v_pk_mul_f32 v[46:47], v[46:47], v[234:235]
	v_pk_mul_f32 v[40:41], v[40:41], v[236:237]
	v_pk_mul_f32 v[42:43], v[42:43], v[238:239]
	v_pk_mul_f32 v[36:37], v[36:37], v[240:241]
	v_pk_mul_f32 v[38:39], v[38:39], v[242:243]
	v_pk_mul_f32 v[32:33], v[32:33], v[248:249]
	v_pk_mul_f32 v[34:35], v[34:35], v[250:251]
	v_pk_mul_f32 v[60:61], v[60:61], v[232:233]
	v_pk_mul_f32 v[62:63], v[62:63], v[234:235]
	v_pk_mul_f32 v[56:57], v[56:57], v[236:237]
	v_pk_mul_f32 v[58:59], v[58:59], v[238:239]
	v_pk_mul_f32 v[52:53], v[52:53], v[240:241]
	v_pk_mul_f32 v[54:55], v[54:55], v[242:243]
	v_pk_mul_f32 v[48:49], v[48:49], v[248:249]
	v_pk_mul_f32 v[50:51], v[50:51], v[250:251]
	v_pk_mul_f32 v[28:29], v[28:29], v[232:233]
	v_pk_mul_f32 v[30:31], v[30:31], v[234:235]
	v_pk_mul_f32 v[24:25], v[24:25], v[236:237]
	v_pk_mul_f32 v[26:27], v[26:27], v[238:239]
	v_pk_mul_f32 v[20:21], v[20:21], v[240:241]
	v_pk_mul_f32 v[22:23], v[22:23], v[242:243]
	v_pk_mul_f32 v[16:17], v[16:17], v[248:249]
	v_pk_mul_f32 v[18:19], v[18:19], v[250:251]
	v_pk_mul_f32 v[12:13], v[12:13], v[232:233]
	v_pk_mul_f32 v[14:15], v[14:15], v[234:235]
	v_pk_mul_f32 v[8:9], v[8:9], v[236:237]
	v_pk_mul_f32 v[10:11], v[10:11], v[238:239]
	v_pk_mul_f32 v[4:5], v[4:5], v[240:241]
	v_pk_mul_f32 v[6:7], v[6:7], v[242:243]
	v_pk_mul_f32 v[0:1], v[0:1], v[248:249]
	v_pk_mul_f32 v[2:3], v[2:3], v[250:251]
; #define SBAR() __builtin_amdgcn_sched_barrier(0)
; __device__ __forceinline__ void partialSM(f32x16& p0, f32x16& p1, float& m_reg, float& mn, float& alpha) {
;     ...
;   for (int r = 0; r < 16; ++r) p0[r] = __builtin_amdgcn_exp2f(p0[r]);
; }
; __device__ __forceinline__ void finishSM(f32x16& p0, f32x16& p1, float alpha, float& l_reg, bf16x8& pa0, bf16x8& pa1, bf16x8& pa2, bf16x8& pa3) {
; #pragma unroll
;   for (int r = 0; r < 16; ++r) p1[r] = __builtin_amdgcn_exp2f(p1[r]);
;   float ps = 0;
; #pragma unroll
;   for (int r = 0; r < 16; ++r) ps += p0[r];
; #pragma unroll
;   for (int r = 0; r < 16; ++r) ps += p1[r];
;   { auto rr = __builtin_amdgcn_permlane32_swap(__float_as_uint(ps), __float_as_uint(ps), false, false);
;     ps = __uint_as_float(rr[0]) + __uint_as_float(rr[1]); }
;   l_reg = l_reg * alpha + ps;
;     ...
;   PK4(p0, 0, pa0); PK4(p0, 8, pa1); PK4(p1, 0, pa2); PK4(p1, 8, pa3);
;     ...
; }
; __device__ __forceinline__ void qkt(f32x16& p0, f32x16& p1, const char* Ks, const bf16x8* qr, const char* qrl, int r32, int hi) {
;   p0 = f32x16{}; p1 = f32x16{};
; #pragma unroll
;   for (int d0 = 0; d0 < 8; ++d0) { int cb = (d0 * 16 + hi * 8) * 2;
;     bf16x8 b0 = *reinterpret_cast<const bf16x8*>(Ks + KSWZ(r32, cb));
;     bf16x8 b1 = *reinterpret_cast<const bf16x8*>(Ks + KSWZ(32 + r32, cb));
;     p0 = __builtin_amdgcn_mfma_f32_32x32x16_bf16(b0, qr[d0], p0, 0, 0, 0);
;     p1 = __builtin_amdgcn_mfma_f32_32x32x16_bf16(b1, qr[d0], p1, 0, 0, 0); }
; #pragma unroll
;   for (int d0 = 8; d0 < 12; ++d0) { int cb = (d0 * 16 + hi * 8) * 2;
;     bf16x8 b0 = *reinterpret_cast<const bf16x8*>(Ks + KSWZ(r32, cb));
;     bf16x8 b1 = *reinterpret_cast<const bf16x8*>(Ks + KSWZ(32 + r32, cb));
;     bf16x8 qf = *reinterpret_cast<const bf16x8*>(qrl + (((2 * (d0 - 8) + hi) ^ ((r32 >> 1) & 7)) << 4));
;     p0 = __builtin_amdgcn_mfma_f32_32x32x16_bf16(b0, qf, p0, 0, 0, 0);
;     p1 = __builtin_amdgcn_mfma_f32_32x32x16_bf16(b1, qf, p1, 0, 0, 0); }
; }
; __device__ __forceinline__ void attn_unit(const bf16_t* __restrict__ Qb, const bf16_t* __restrict__ Kn, const bf16_t* __restrict__ Vh, const bf16_t* __restrict__ Kr,
;                                           bf16_t* GO, int seq, char* lds, const int tid) {
;     ...
;     SWRITE(bp, 0); if (j + 3 < NT) SLOAD(0, (j + 3) * KVBLK); SBAR();
.Lattn_skip_rs1p:
	s_waitcnt lgkmcnt(0)
	s_barrier
	ds_read_b128 v[64:67], v199 offset:12288
	ds_read_b128 v[68:71], v199 offset:24576
	ds_read_b128 v[232:235], v205 offset:12288
	ds_read_b128 v[236:239], v205 offset:24576
	ds_read_b128 v[240:243], v206 offset:12288
	ds_read_b128 v[248:251], v206 offset:24576
	v_exp_f32_e32 v225, v225
	v_exp_f32_e32 v228, v228
	v_exp_f32_e32 v226, v226
	v_add_f32_e32 v211, v225, v228
	s_waitcnt lgkmcnt(4)
	v_mfma_f32_32x32x16_bf16 v[80:95], v[64:67], v[124:127], 0
	v_exp_f32_e32 v229, v229
	v_add_f32_e32 v211, v226, v211
	v_exp_f32_e32 v227, v227
	v_add_f32_e32 v211, v229, v211
	v_mfma_f32_32x32x16_bf16 v[64:79], v[68:71], v[124:127], 0
	v_exp_f32_e32 v230, v230
	v_add_f32_e32 v211, v227, v211
	v_exp_f32_e32 v223, v223
	v_add_f32_e32 v211, v230, v211
	s_waitcnt lgkmcnt(2)
	v_mfma_f32_32x32x16_bf16 v[80:95], v[232:235], v[120:123], v[80:95]
	ds_read_b128 v[232:235], v208 offset:12288
	v_exp_f32_e32 v224, v224
	v_add_f32_e32 v211, v223, v211
	v_exp_f32_e32 v219, v219
	v_add_f32_e32 v211, v224, v211
	v_mfma_f32_32x32x16_bf16 v[64:79], v[236:239], v[120:123], v[64:79]
	ds_read_b128 v[236:239], v208 offset:24576
	v_exp_f32_e32 v221, v221
	v_add_f32_e32 v211, v219, v211
	v_exp_f32_e32 v220, v220
	v_add_f32_e32 v211, v221, v211
	s_waitcnt lgkmcnt(2)
	v_mfma_f32_32x32x16_bf16 v[80:95], v[240:243], v[116:119], v[80:95]
	ds_read_b128 v[240:243], v207 offset:12288
	v_exp_f32_e32 v222, v222
	v_add_f32_e32 v211, v220, v211
	v_exp_f32_e32 v215, v215
	v_add_f32_e32 v211, v222, v211
	v_mfma_f32_32x32x16_bf16 v[64:79], v[248:251], v[116:119], v[64:79]
	ds_read_b128 v[248:251], v207 offset:24576
	v_exp_f32_e32 v217, v217
	v_add_f32_e32 v211, v215, v211
	v_exp_f32_e32 v216, v216
	v_add_f32_e32 v211, v217, v211
	s_waitcnt lgkmcnt(2)
	v_mfma_f32_32x32x16_bf16 v[80:95], v[232:235], v[112:115], v[80:95]
	ds_read_b128 v[232:235], v204 offset:12288
	v_exp_f32_e32 v218, v218
	v_add_f32_e32 v211, v216, v211
	v_exp_f32_e32 v162, v162
	v_add_f32_e32 v211, v218, v211
	v_mfma_f32_32x32x16_bf16 v[64:79], v[236:239], v[112:115], v[64:79]
	ds_read_b128 v[236:239], v204 offset:24576
	v_exp_f32_e32 v163, v163
	v_exp_f32_e32 v160, v160
	v_exp_f32_e32 v161, v161
	s_waitcnt lgkmcnt(2)
	v_mfma_f32_32x32x16_bf16 v[80:95], v[240:243], v[108:111], v[80:95]
	ds_read_b128 v[240:243], v203 offset:12288
	v_exp_f32_e32 v158, v158
	v_exp_f32_e32 v159, v159
	v_exp_f32_e32 v156, v156
	v_mfma_f32_32x32x16_bf16 v[64:79], v[248:251], v[108:111], v[64:79]
	ds_read_b128 v[248:251], v203 offset:24576
	v_exp_f32_e32 v157, v157
	v_exp_f32_e32 v154, v154
	v_exp_f32_e32 v155, v155
	s_waitcnt lgkmcnt(2)
	v_mfma_f32_32x32x16_bf16 v[80:95], v[232:235], v[104:107], v[80:95]
	ds_read_b128 v[232:235], v200 offset:12288
	v_exp_f32_e32 v152, v152
	v_exp_f32_e32 v153, v153
	v_exp_f32_e32 v150, v150
	v_mfma_f32_32x32x16_bf16 v[64:79], v[236:239], v[104:107], v[64:79]
	ds_read_b128 v[236:239], v200 offset:24576
	v_exp_f32_e32 v151, v151
	v_exp_f32_e32 v148, v148
	v_exp_f32_e32 v149, v149
	s_waitcnt lgkmcnt(2)
	v_mfma_f32_32x32x16_bf16 v[80:95], v[240:243], v[100:103], v[80:95]
	ds_read_b128 v[240:243], v191 offset:12288
	v_add_f32_e32 v212, v162, v163
	v_add_f32_e32 v212, v160, v212
	v_add_f32_e32 v212, v161, v212
	v_add_f32_e32 v212, v158, v212
	v_add_f32_e32 v212, v159, v212
	v_add_f32_e32 v212, v156, v212
	v_mfma_f32_32x32x16_bf16 v[64:79], v[248:251], v[100:103], v[64:79]
	ds_read_b128 v[248:251], v202 offset:24576
	v_add_f32_e32 v212, v157, v212
	v_add_f32_e32 v212, v154, v212
	v_add_f32_e32 v212, v155, v212
	v_add_f32_e32 v212, v152, v212
	v_add_f32_e32 v212, v153, v212
	v_add_f32_e32 v212, v150, v212
	s_waitcnt lgkmcnt(2)
	v_mfma_f32_32x32x16_bf16 v[80:95], v[232:235], v[96:99], v[80:95]
	ds_read_b128 v[232:235], v182
	v_add_f32_e32 v212, v151, v212
	v_add_f32_e32 v212, v148, v212
	v_add_f32_e32 v212, v149, v212
	v_add_f32_e32 v211, v211, v212
	v_mov_b32_e32 v212, v211
	v_add_u32_e32 v194, s31, v183
	s_waitcnt vmcnt(4)
	v_mfma_f32_32x32x16_bf16 v[64:79], v[236:239], v[96:99], v[64:79]
	ds_read_b128 v[236:239], v198 offset:12288
	ds_write_b128 v194, v[140:143]
	v_add_u32_e32 v194, s31, v184
	s_add_i32 s73, s73, 2
	s_cmp_ge_u32 s73, s45
	s_waitcnt vmcnt(2)
	ds_write_b128 v194, v[144:147]
	s_cselect_b64 s[28:29], -1, 0
	ds_write_b128 v185, v[136:139] offset:36864
	s_waitcnt vmcnt(1)
	ds_write_b128 v185, v[132:135] offset:49152
	s_and_b64 vcc, exec, s[28:29]
	s_waitcnt lgkmcnt(5)
	v_mfma_f32_32x32x16_bf16 v[80:95], v[240:243], v[232:235], v[80:95]
	ds_read_b128 v[240:243], v201 offset:24576
	s_waitcnt vmcnt(0)
	ds_write_b128 v186, v[128:131] offset:36864
	v_mfma_f32_32x32x16_bf16 v[64:79], v[248:251], v[232:235], v[64:79]
	ds_read_b128 v[248:251], v181
	ds_read_b128 v[232:235], v187 offset:12288
	s_cbranch_vccnz .Lattn_noloadp
	v_add_co_u32_e32 v128, vcc, 0xfffe0000, v168
	s_nop 1
	v_addc_co_u32_e32 v129, vcc, -1, v169, vcc
	global_load_dwordx4 v[140:143], v[128:129], off
	global_load_dwordx4 v[136:139], v[128:129], off offset:-256
	global_load_dwordx4 v[144:147], v[168:169], off
	global_load_dwordx4 v[132:135], v[168:169], off offset:-256
	s_nop 0
	global_load_dwordx4 v[128:131], v[166:167], off
; __device__ __forceinline__ void partialSM(f32x16& p0, f32x16& p1, float& m_reg, float& mn, float& alpha) {
;   constexpr float C = SCALE * 1.4426950408889634f;
;   float pmax = p0[0];
; #pragma unroll
;   for (int r = 1; r < 16; ++r) pmax = fmaxf(pmax, p0[r]);
; #pragma unroll
;   for (int r = 0; r < 16; ++r) pmax = fmaxf(pmax, p1[r]);
;   { auto rr = __builtin_amdgcn_permlane32_swap(__float_as_uint(pmax), __float_as_uint(pmax), false, false);
;     pmax = fmaxf(__uint_as_float(rr[0]), __uint_as_float(rr[1])); }
;   if (__builtin_expect(__all(pmax - m_reg <= THR / SCALE), 1)) { mn = m_reg; alpha = 1.f; }
;   else { mn = fmaxf(m_reg, pmax); alpha = __builtin_amdgcn_exp2f((m_reg - mn) * C); m_reg = mn; }
;   float mnC = -mn * C;
; #pragma unroll
;   for (int r = 0; r < 16; ++r) p0[r] = fmaf(p0[r], C, mnC);
; #pragma unroll
;   for (int r = 0; r < 16; ++r) p1[r] = fmaf(p1[r], C, mnC);
; #pragma unroll
;   for (int r = 0; r < 16; ++r) p0[r] = __builtin_amdgcn_exp2f(p0[r]);
; }
; __device__ __forceinline__ void finishSM(f32x16& p0, f32x16& p1, float alpha, float& l_reg, bf16x8& pa0, bf16x8& pa1, bf16x8& pa2, bf16x8& pa3) {
; #pragma unroll
;   for (int r = 0; r < 16; ++r) p1[r] = __builtin_amdgcn_exp2f(p1[r]);
;   float ps = 0;
; #pragma unroll
;   for (int r = 0; r < 16; ++r) ps += p0[r];
; #pragma unroll
;   for (int r = 0; r < 16; ++r) ps += p1[r];
;   { auto rr = __builtin_amdgcn_permlane32_swap(__float_as_uint(ps), __float_as_uint(ps), false, false);
;     ps = __uint_as_float(rr[0]) + __uint_as_float(rr[1]); }
;   l_reg = l_reg * alpha + ps;
;     ...
;   PK4(p0, 0, pa0); PK4(p0, 8, pa1); PK4(p1, 0, pa2); PK4(p1, 8, pa3);
;     ...
; }
.Lattn_noloadp:
	s_waitcnt lgkmcnt(1)
	v_mfma_f32_32x32x16_bf16 v[80:95], v[236:239], v[248:251], v[80:95]
	ds_read_b128 v[236:239], v189 offset:24576
	v_cvt_pk_bf16_f32 v158, v158, v159
	v_cvt_pk_bf16_f32 v159, v156, v157
	v_permlane32_swap_b32_e32 v211, v212
	v_cvt_pk_bf16_f32 v156, v162, v163
	v_cvt_pk_bf16_f32 v157, v160, v161
	v_cvt_pk_bf16_f32 v160, v154, v155
	v_mfma_f32_32x32x16_bf16 v[64:79], v[240:243], v[248:251], v[64:79]
	ds_read_b128 v[240:243], v179
	ds_read_b128 v[248:251], v188 offset:12288
	v_cvt_pk_bf16_f32 v161, v152, v153
	v_cvt_pk_bf16_f32 v162, v150, v151
	v_cvt_pk_bf16_f32 v163, v148, v149
	v_add_f32_e32 v211, v211, v212
	v_cvt_pk_bf16_f32 v148, v225, v228
	v_cvt_pk_bf16_f32 v149, v226, v229
	s_waitcnt lgkmcnt(1)
	v_mfma_f32_32x32x16_bf16 v[80:95], v[232:235], v[240:243], v[80:95]
	ds_read_b128 v[232:235], v190 offset:24576
	v_cvt_pk_bf16_f32 v150, v227, v230
	v_cvt_pk_bf16_f32 v151, v223, v224
	v_cvt_pk_bf16_f32 v152, v219, v221
	v_cvt_pk_bf16_f32 v153, v220, v222
	v_cvt_pk_bf16_f32 v154, v215, v217
	v_cvt_pk_bf16_f32 v155, v216, v218
	v_mfma_f32_32x32x16_bf16 v[64:79], v[236:239], v[240:243], v[64:79]
	ds_read_b128 v[236:239], v177
	v_fma_f32 v176, v214, v176, v211
	s_waitcnt lgkmcnt(0)
	v_mfma_f32_32x32x16_bf16 v[80:95], v[248:251], v[236:239], v[80:95]
	v_mfma_f32_32x32x16_bf16 v[64:79], v[232:235], v[236:239], v[64:79]
	v_lshl_add_u32 v231, s76, 14, v178
	ds_read_b64_tr_b16 v[240:241], v231 offset:0
	ds_read_b64_tr_b16 v[242:243], v231 offset:2048
	ds_read_b64_tr_b16 v[248:249], v231 offset:512
	ds_read_b64_tr_b16 v[250:251], v231 offset:2560
	ds_read_b64_tr_b16 v[232:233], v231 offset:1024
	ds_read_b64_tr_b16 v[234:235], v231 offset:3072
	ds_read_b64_tr_b16 v[236:237], v231 offset:1536
	ds_read_b64_tr_b16 v[238:239], v231 offset:3584
	s_nop 3
	v_max3_f32 v194, v80, v81, v82
	v_max3_f32 v195, v64, v65, v66
	v_max3_f32 v194, v194, v83, v84
	v_max3_f32 v195, v195, v67, v68
	s_waitcnt lgkmcnt(4)
	v_mfma_f32_32x32x16_bf16 v[32:47], v[148:151], v[240:243], v[32:47]
	ds_read_b64_tr_b16 v[240:241], v231 offset:4096
	ds_read_b64_tr_b16 v[242:243], v231 offset:6144
	v_max3_f32 v194, v194, v85, v86
	v_max3_f32 v195, v195, v69, v70
	v_max3_f32 v194, v194, v87, v88
	v_max3_f32 v195, v195, v71, v72
	v_mfma_f32_32x32x16_bf16 v[48:63], v[148:151], v[248:251], v[48:63]
	ds_read_b64_tr_b16 v[248:249], v231 offset:4608
	ds_read_b64_tr_b16 v[250:251], v231 offset:6656
	v_max3_f32 v194, v194, v89, v90
	v_max3_f32 v195, v195, v73, v74
	v_max3_f32 v194, v194, v91, v92
	v_max3_f32 v195, v195, v75, v76
	s_waitcnt lgkmcnt(4)
	v_mfma_f32_32x32x16_bf16 v[16:31], v[148:151], v[232:235], v[16:31]
	ds_read_b64_tr_b16 v[232:233], v231 offset:5120
	ds_read_b64_tr_b16 v[234:235], v231 offset:7168
	v_max3_f32 v194, v194, v93, v94
	v_max3_f32 v195, v195, v77, v78
	v_max3_f32 v194, v194, v95, v195
	v_max_f32_e32 v194, v194, v79
	v_mfma_f32_32x32x16_bf16 v[0:15], v[148:151], v[236:239], v[0:15]
	ds_read_b64_tr_b16 v[236:237], v231 offset:5632
	ds_read_b64_tr_b16 v[238:239], v231 offset:7680
	v_mov_b32_e32 v195, v194
	s_nop 1
	v_permlane32_swap_b32_e32 v194, v195
	v_max_f32_e32 v194, v194, v195
	s_waitcnt lgkmcnt(4)
	v_mfma_f32_32x32x16_bf16 v[32:47], v[152:155], v[240:243], v[32:47]
	ds_read_b64_tr_b16 v[240:241], v231 offset:8192
	ds_read_b64_tr_b16 v[242:243], v231 offset:10240
	v_sub_f32_e32 v195, v194, v210
	v_cmp_ge_f32_e32 vcc, s15, v195
	v_mfma_f32_32x32x16_bf16 v[48:63], v[152:155], v[248:251], v[48:63]
	ds_read_b64_tr_b16 v[248:249], v231 offset:8704
	ds_read_b64_tr_b16 v[250:251], v231 offset:10752
	s_cmp_eq_u64 vcc, exec
	s_cselect_b64 s[40:41], -1, 0
	s_cbranch_scc1 .Lattn_fast2p
	v_max_f32_e32 v194, v210, v194
	v_sub_f32_e32 v195, v210, v194
	v_mul_f32_e32 v195, 0x3dd53b94, v195
	v_exp_f32_e32 v213, v195
	v_mov_b32_e32 v210, v194
	s_branch .Lattn_join2p

; #define SBAR() __builtin_amdgcn_sched_barrier(0)
; template <int D0> __device__ __forceinline__ void pv_one(f32x16& od, int vb, bf16x8 pa0, bf16x8 pa1, bf16x8 pa2, bf16x8 pa3) {
;   const s16x4 l0 = tr_read<v_rd_off(D0, 0, 0)>(vb), h0 = tr_read<v_rd_off(D0, 0, 1)>(vb), l1 = tr_read<v_rd_off(D0, 1, 0)>(vb), h1 = tr_read<v_rd_off(D0, 1, 1)>(vb);
;   const s16x4 l2 = tr_read<v_rd_off(D0, 2, 0)>(vb), h2 = tr_read<v_rd_off(D0, 2, 1)>(vb), l3 = tr_read<v_rd_off(D0, 3, 0)>(vb), h3 = tr_read<v_rd_off(D0, 3, 1)>(vb);
;   asm volatile("s_waitcnt lgkmcnt(0)" ::: "memory"); SBAR();
;     ...
;   od = __builtin_amdgcn_mfma_f32_32x32x16_bf16(pa0, PK(l0, h0), od, 0, 0, 0);
;   od = __builtin_amdgcn_mfma_f32_32x32x16_bf16(pa1, PK(l1, h1), od, 0, 0, 0);
;   od = __builtin_amdgcn_mfma_f32_32x32x16_bf16(pa2, PK(l2, h2), od, 0, 0, 0);
;   od = __builtin_amdgcn_mfma_f32_32x32x16_bf16(pa3, PK(l3, h3), od, 0, 0, 0);
;     ...
; }
; __device__ __forceinline__ void pv_d0(f32x16* o, int vb, bf16x8 pa0, bf16x8 pa1, bf16x8 pa2, bf16x8 pa3) {
;   pv_one<0>(o[0], vb, pa0, pa1, pa2, pa3); pv_one<1>(o[1], vb, pa0, pa1, pa2, pa3); pv_one<2>(o[2], vb, pa0, pa1, pa2, pa3); pv_one<3>(o[3], vb, pa0, pa1, pa2, pa3);
.Lattn_join2p:
	v_mul_f32_e32 v194, 0xbdd53b94, v210
	s_waitcnt lgkmcnt(4)
	v_mfma_f32_32x32x16_bf16 v[16:31], v[152:155], v[232:235], v[16:31]
	ds_read_b64_tr_b16 v[232:233], v231 offset:9216
	ds_read_b64_tr_b16 v[234:235], v231 offset:11264
	v_fmamk_f32 v225, v80, 0x3dd53b94, v194
	v_fmamk_f32 v228, v81, 0x3dd53b94, v194
	v_fmamk_f32 v226, v82, 0x3dd53b94, v194
	v_fmamk_f32 v229, v83, 0x3dd53b94, v194
	v_mfma_f32_32x32x16_bf16 v[0:15], v[152:155], v[236:239], v[0:15]
	ds_read_b64_tr_b16 v[236:237], v231 offset:9728
	ds_read_b64_tr_b16 v[238:239], v231 offset:11776
	v_fmamk_f32 v150, v76, 0x3dd53b94, v194
	v_fmamk_f32 v151, v77, 0x3dd53b94, v194
	v_fmamk_f32 v148, v78, 0x3dd53b94, v194
	v_fmamk_f32 v149, v79, 0x3dd53b94, v194
	s_waitcnt lgkmcnt(4)
	v_mfma_f32_32x32x16_bf16 v[32:47], v[156:159], v[240:243], v[32:47]
	ds_read_b64_tr_b16 v[240:241], v231 offset:12288
	ds_read_b64_tr_b16 v[242:243], v231 offset:14336
	v_fmamk_f32 v227, v84, 0x3dd53b94, v194
	v_fmamk_f32 v230, v85, 0x3dd53b94, v194
	v_fmamk_f32 v223, v86, 0x3dd53b94, v194
	v_fmamk_f32 v224, v87, 0x3dd53b94, v194
	v_mfma_f32_32x32x16_bf16 v[48:63], v[156:159], v[248:251], v[48:63]
	ds_read_b64_tr_b16 v[248:249], v231 offset:12800
	ds_read_b64_tr_b16 v[250:251], v231 offset:14848
	v_fmamk_f32 v154, v72, 0x3dd53b94, v194
	v_fmamk_f32 v155, v73, 0x3dd53b94, v194
	v_fmamk_f32 v152, v74, 0x3dd53b94, v194
	v_fmamk_f32 v153, v75, 0x3dd53b94, v194
	s_waitcnt lgkmcnt(4)
	v_mfma_f32_32x32x16_bf16 v[16:31], v[156:159], v[232:235], v[16:31]
	ds_read_b64_tr_b16 v[232:233], v231 offset:13312
	ds_read_b64_tr_b16 v[234:235], v231 offset:15360
	v_fmamk_f32 v219, v88, 0x3dd53b94, v194
	v_fmamk_f32 v221, v89, 0x3dd53b94, v194
	v_fmamk_f32 v220, v90, 0x3dd53b94, v194
	v_fmamk_f32 v222, v91, 0x3dd53b94, v194
	v_mfma_f32_32x32x16_bf16 v[0:15], v[156:159], v[236:239], v[0:15]
	ds_read_b64_tr_b16 v[236:237], v231 offset:13824
	ds_read_b64_tr_b16 v[238:239], v231 offset:15872
	v_fmamk_f32 v158, v68, 0x3dd53b94, v194
	v_fmamk_f32 v159, v69, 0x3dd53b94, v194
	v_fmamk_f32 v156, v70, 0x3dd53b94, v194
	v_fmamk_f32 v157, v71, 0x3dd53b94, v194
	s_waitcnt lgkmcnt(4)
	v_mfma_f32_32x32x16_bf16 v[32:47], v[160:163], v[240:243], v[32:47]
	v_fmamk_f32 v215, v92, 0x3dd53b94, v194
	v_fmamk_f32 v217, v93, 0x3dd53b94, v194
	v_fmamk_f32 v216, v94, 0x3dd53b94, v194
	v_fmamk_f32 v218, v95, 0x3dd53b94, v194
	v_mfma_f32_32x32x16_bf16 v[48:63], v[160:163], v[248:251], v[48:63]
	s_waitcnt lgkmcnt(0)
	v_mfma_f32_32x32x16_bf16 v[16:31], v[160:163], v[232:235], v[16:31]
	v_mfma_f32_32x32x16_bf16 v[0:15], v[160:163], v[236:239], v[0:15]
	v_fmamk_f32 v162, v64, 0x3dd53b94, v194
	v_fmamk_f32 v163, v65, 0x3dd53b94, v194
	v_fmamk_f32 v160, v66, 0x3dd53b94, v194
	v_fmamk_f32 v161, v67, 0x3dd53b94, v194
	s_and_b64 vcc, exec, s[40:41]
	s_cbranch_vccnz .Lattn_skip_rs2p
	s_and_saveexec_b64 s[18:19], s[38:39]
	ds_write_b32 v175, v213 offset:128
	s_or_b64 exec, exec, s[18:19]
	s_waitcnt lgkmcnt(0)
	v_add_u32_e32 v194, v173, v164
	ds_read_b128 v[232:235], v194 offset:224
	ds_read_b128 v[236:239], v194 offset:192
	ds_read_b128 v[240:243], v194 offset:160
	ds_read_b128 v[248:251], v194 offset:128
	s_waitcnt lgkmcnt(0)
	v_pk_mul_f32 v[44:45], v[44:45], v[232:233]
	v_pk_mul_f32 v[46:47], v[46:47], v[234:235]
	v_pk_mul_f32 v[40:41], v[40:41], v[236:237]
	v_pk_mul_f32 v[42:43], v[42:43], v[238:239]
	v_pk_mul_f32 v[36:37], v[36:37], v[240:241]
	v_pk_mul_f32 v[38:39], v[38:39], v[242:243]
	v_pk_mul_f32 v[32:33], v[32:33], v[248:249]
	v_pk_mul_f32 v[34:35], v[34:35], v[250:251]
	v_pk_mul_f32 v[60:61], v[60:61], v[232:233]
	v_pk_mul_f32 v[62:63], v[62:63], v[234:235]
	v_pk_mul_f32 v[56:57], v[56:57], v[236:237]
	v_pk_mul_f32 v[58:59], v[58:59], v[238:239]
	v_pk_mul_f32 v[52:53], v[52:53], v[240:241]
	v_pk_mul_f32 v[54:55], v[54:55], v[242:243]
	v_pk_mul_f32 v[48:49], v[48:49], v[248:249]
	v_pk_mul_f32 v[50:51], v[50:51], v[250:251]
	v_pk_mul_f32 v[28:29], v[28:29], v[232:233]
	v_pk_mul_f32 v[30:31], v[30:31], v[234:235]
	v_pk_mul_f32 v[24:25], v[24:25], v[236:237]
	v_pk_mul_f32 v[26:27], v[26:27], v[238:239]
	v_pk_mul_f32 v[20:21], v[20:21], v[240:241]
	v_pk_mul_f32 v[22:23], v[22:23], v[242:243]
	v_pk_mul_f32 v[16:17], v[16:17], v[248:249]
	v_pk_mul_f32 v[18:19], v[18:19], v[250:251]
	v_pk_mul_f32 v[12:13], v[12:13], v[232:233]
	v_pk_mul_f32 v[14:15], v[14:15], v[234:235]
	v_pk_mul_f32 v[8:9], v[8:9], v[236:237]
	v_pk_mul_f32 v[10:11], v[10:11], v[238:239]
	v_pk_mul_f32 v[4:5], v[4:5], v[240:241]
	v_pk_mul_f32 v[6:7], v[6:7], v[242:243]
	v_pk_mul_f32 v[0:1], v[0:1], v[248:249]
	v_pk_mul_f32 v[2:3], v[2:3], v[250:251]

; __device__ __forceinline__ void finishSM(f32x16& p0, f32x16& p1, float alpha, float& l_reg, bf16x8& pa0, bf16x8& pa1, bf16x8& pa2, bf16x8& pa3) {
; #pragma unroll
;   for (int r = 0; r < 16; ++r) p1[r] = __builtin_amdgcn_exp2f(p1[r]);
;   float ps = 0;
; #pragma unroll
;   for (int r = 0; r < 16; ++r) ps += p0[r];
; #pragma unroll
;   for (int r = 0; r < 16; ++r) ps += p1[r];
;   { auto rr = __builtin_amdgcn_permlane32_swap(__float_as_uint(ps), __float_as_uint(ps), false, false);
;     ps = __uint_as_float(rr[0]) + __uint_as_float(rr[1]); }
;   l_reg = l_reg * alpha + ps;
;     ...
;   PK4(p0, 0, pa0); PK4(p0, 8, pa1); PK4(p1, 0, pa2); PK4(p1, 8, pa3);
;     ...
; }
; __device__ __forceinline__ void qkt(f32x16& p0, f32x16& p1, const char* Ks, const bf16x8* qr, const char* qrl, int r32, int hi) {
;   p0 = f32x16{}; p1 = f32x16{};
; #pragma unroll
;   for (int d0 = 0; d0 < 8; ++d0) { int cb = (d0 * 16 + hi * 8) * 2;
;     bf16x8 b0 = *reinterpret_cast<const bf16x8*>(Ks + KSWZ(r32, cb));
;     bf16x8 b1 = *reinterpret_cast<const bf16x8*>(Ks + KSWZ(32 + r32, cb));
;     p0 = __builtin_amdgcn_mfma_f32_32x32x16_bf16(b0, qr[d0], p0, 0, 0, 0);
;     p1 = __builtin_amdgcn_mfma_f32_32x32x16_bf16(b1, qr[d0], p1, 0, 0, 0); }
; #pragma unroll
;   for (int d0 = 8; d0 < 12; ++d0) { int cb = (d0 * 16 + hi * 8) * 2;
;     bf16x8 b0 = *reinterpret_cast<const bf16x8*>(Ks + KSWZ(r32, cb));
;     bf16x8 b1 = *reinterpret_cast<const bf16x8*>(Ks + KSWZ(32 + r32, cb));
;     bf16x8 qf = *reinterpret_cast<const bf16x8*>(qrl + (((2 * (d0 - 8) + hi) ^ ((r32 >> 1) & 7)) << 4));
;     p0 = __builtin_amdgcn_mfma_f32_32x32x16_bf16(b0, qf, p0, 0, 0, 0);
;     p1 = __builtin_amdgcn_mfma_f32_32x32x16_bf16(b1, qf, p1, 0, 0, 0); }
; }
.Lattn_steady:
	s_sub_i32 s30, s76, 1
	s_cmp_eq_u32 s76, 0
	s_cselect_b32 s30, 2, s30
	s_add_i32 s18, s76, 1
	s_cmp_lg_u32 s76, 2
	s_cselect_b32 s18, s18, 0
	ds_read_b128 v[64:67], v199 offset:36864
	ds_read_b128 v[68:71], v199 offset:49152
	ds_read_b128 v[232:235], v205 offset:36864
	ds_read_b128 v[236:239], v205 offset:49152
	ds_read_b128 v[240:243], v206 offset:36864
	ds_read_b128 v[248:251], v206 offset:49152
	v_exp_f32_e32 v225, v225
	v_exp_f32_e32 v228, v228
	v_exp_f32_e32 v226, v226
	v_add_f32_e32 v211, v225, v228
	s_waitcnt lgkmcnt(4)
	v_mfma_f32_32x32x16_bf16 v[80:95], v[64:67], v[124:127], 0
	v_exp_f32_e32 v229, v229
	v_add_f32_e32 v211, v226, v211
	v_exp_f32_e32 v227, v227
	v_add_f32_e32 v211, v229, v211
	v_mfma_f32_32x32x16_bf16 v[64:79], v[68:71], v[124:127], 0
	v_exp_f32_e32 v230, v230
	v_add_f32_e32 v211, v227, v211
	v_exp_f32_e32 v223, v223
	v_add_f32_e32 v211, v230, v211
	s_waitcnt lgkmcnt(2)
	v_mfma_f32_32x32x16_bf16 v[80:95], v[232:235], v[120:123], v[80:95]
	ds_read_b128 v[232:235], v208 offset:36864
	v_exp_f32_e32 v224, v224
	v_add_f32_e32 v211, v223, v211
	v_exp_f32_e32 v219, v219
	v_add_f32_e32 v211, v224, v211
	v_mfma_f32_32x32x16_bf16 v[64:79], v[236:239], v[120:123], v[64:79]
	ds_read_b128 v[236:239], v208 offset:49152
	v_exp_f32_e32 v221, v221
	v_add_f32_e32 v211, v219, v211
	v_exp_f32_e32 v220, v220
	v_add_f32_e32 v211, v221, v211
	s_waitcnt lgkmcnt(2)
	v_mfma_f32_32x32x16_bf16 v[80:95], v[240:243], v[116:119], v[80:95]
	ds_read_b128 v[240:243], v207 offset:36864
	v_exp_f32_e32 v222, v222
	v_add_f32_e32 v211, v220, v211
	v_exp_f32_e32 v215, v215
	v_add_f32_e32 v211, v222, v211
	v_mfma_f32_32x32x16_bf16 v[64:79], v[248:251], v[116:119], v[64:79]
	ds_read_b128 v[248:251], v207 offset:49152
	v_exp_f32_e32 v217, v217
	v_add_f32_e32 v211, v215, v211
	v_exp_f32_e32 v216, v216
	v_add_f32_e32 v211, v217, v211
	s_waitcnt lgkmcnt(2)
	v_mfma_f32_32x32x16_bf16 v[80:95], v[232:235], v[112:115], v[80:95]
	ds_read_b128 v[232:235], v204 offset:36864
	v_exp_f32_e32 v218, v218
	v_add_f32_e32 v211, v216, v211
	v_exp_f32_e32 v162, v162
	v_add_f32_e32 v211, v218, v211
	v_mfma_f32_32x32x16_bf16 v[64:79], v[236:239], v[112:115], v[64:79]
	ds_read_b128 v[236:239], v204 offset:49152
	v_exp_f32_e32 v163, v163
	v_exp_f32_e32 v160, v160
	v_exp_f32_e32 v161, v161
	s_waitcnt lgkmcnt(2)
	v_mfma_f32_32x32x16_bf16 v[80:95], v[240:243], v[108:111], v[80:95]
	ds_read_b128 v[240:243], v203 offset:36864
	v_exp_f32_e32 v158, v158
	v_exp_f32_e32 v159, v159
	v_exp_f32_e32 v156, v156
	v_mfma_f32_32x32x16_bf16 v[64:79], v[248:251], v[108:111], v[64:79]
	ds_read_b128 v[248:251], v203 offset:49152
	v_exp_f32_e32 v157, v157
	v_exp_f32_e32 v154, v154
	v_exp_f32_e32 v155, v155
	s_waitcnt lgkmcnt(2)
	v_mfma_f32_32x32x16_bf16 v[80:95], v[232:235], v[104:107], v[80:95]
	ds_read_b128 v[232:235], v200 offset:36864
	v_exp_f32_e32 v152, v152
	v_exp_f32_e32 v153, v153
	v_exp_f32_e32 v150, v150
	v_mfma_f32_32x32x16_bf16 v[64:79], v[236:239], v[104:107], v[64:79]
	ds_read_b128 v[236:239], v200 offset:49152
	v_exp_f32_e32 v151, v151
	v_exp_f32_e32 v148, v148
	v_exp_f32_e32 v149, v149
	s_waitcnt lgkmcnt(2)
	v_mfma_f32_32x32x16_bf16 v[80:95], v[240:243], v[100:103], v[80:95]
	ds_read_b128 v[240:243], v191 offset:36864
	v_add_f32_e32 v212, v162, v163
	v_add_f32_e32 v212, v160, v212
	v_add_f32_e32 v212, v161, v212
	v_add_f32_e32 v212, v158, v212
	v_add_f32_e32 v212, v159, v212
	v_add_f32_e32 v212, v156, v212
	v_mfma_f32_32x32x16_bf16 v[64:79], v[248:251], v[100:103], v[64:79]
	ds_read_b128 v[248:251], v202 offset:49152
	v_add_f32_e32 v212, v157, v212
	v_add_f32_e32 v212, v154, v212
	v_add_f32_e32 v212, v155, v212
	v_add_f32_e32 v212, v152, v212
	v_add_f32_e32 v212, v153, v212
	v_add_f32_e32 v212, v150, v212
	s_waitcnt lgkmcnt(2)
	v_mfma_f32_32x32x16_bf16 v[80:95], v[232:235], v[96:99], v[80:95]
	ds_read_b128 v[232:235], v182
	v_add_f32_e32 v212, v151, v212
	v_add_f32_e32 v212, v148, v212
	v_add_f32_e32 v212, v149, v212
	v_add_f32_e32 v211, v211, v212
	v_mov_b32_e32 v212, v211
	s_lshl_b32 s19, s18, 14
	v_add_u32_e32 v231, s19, v183
	s_waitcnt vmcnt(0)
	v_mfma_f32_32x32x16_bf16 v[64:79], v[236:239], v[96:99], v[64:79]
	ds_read_b128 v[236:239], v198 offset:36864
	ds_write_b128 v231, v[140:143]
	v_add_u32_e32 v140, s19, v184
	ds_write_b128 v140, v[144:147]
	ds_write_b128 v185, v[136:139] offset:12288
	ds_write_b128 v185, v[132:135] offset:24576
	s_mov_b32 s18, 0xfffa0000
	ds_write_b128 v186, v[128:131] offset:12288
	v_add_co_u32_e32 v128, vcc, s18, v168
	s_mov_b32 s18, 0xfffc0000
	s_nop 0
	s_waitcnt lgkmcnt(6)
; __device__ __forceinline__ void qkt(f32x16& p0, f32x16& p1, const char* Ks, const bf16x8* qr, const char* qrl, int r32, int hi) {
;   p0 = f32x16{}; p1 = f32x16{};
; #pragma unroll
;   for (int d0 = 0; d0 < 8; ++d0) { int cb = (d0 * 16 + hi * 8) * 2;
;     bf16x8 b0 = *reinterpret_cast<const bf16x8*>(Ks + KSWZ(r32, cb));
;     bf16x8 b1 = *reinterpret_cast<const bf16x8*>(Ks + KSWZ(32 + r32, cb));
;     p0 = __builtin_amdgcn_mfma_f32_32x32x16_bf16(b0, qr[d0], p0, 0, 0, 0);
;     p1 = __builtin_amdgcn_mfma_f32_32x32x16_bf16(b1, qr[d0], p1, 0, 0, 0); }
; #pragma unroll
;   for (int d0 = 8; d0 < 12; ++d0) { int cb = (d0 * 16 + hi * 8) * 2;
;     bf16x8 b0 = *reinterpret_cast<const bf16x8*>(Ks + KSWZ(r32, cb));
;     bf16x8 b1 = *reinterpret_cast<const bf16x8*>(Ks + KSWZ(32 + r32, cb));
;     bf16x8 qf = *reinterpret_cast<const bf16x8*>(qrl + (((2 * (d0 - 8) + hi) ^ ((r32 >> 1) & 7)) << 4));
;     p0 = __builtin_amdgcn_mfma_f32_32x32x16_bf16(b0, qf, p0, 0, 0, 0);
;     p1 = __builtin_amdgcn_mfma_f32_32x32x16_bf16(b1, qf, p1, 0, 0, 0); }
; }
; __device__ __forceinline__ int v_st(int k, int c) { const int kk = (k & ~0xC) | ((k & 4) << 1) | ((k & 8) >> 1); return ((kk >> 3) * 4 + (c >> 5)) * 512 + ((kk & 7) * 32 + (c & 31)) * 2; }
; __device__ __forceinline__ int v_rd_base(int lane) { return ((lane & 3) << 3) | (((lane >> 2) & 3) << 6) | (((lane >> 4) & 1) << 5) | (((lane >> 5) & 1) << 8); }
; template <int OFF> __device__ __forceinline__ s16x4 tr_read(int vb) {
;   s16x4 r; asm volatile("ds_read_b64_tr_b16 %0, %1 offset:%2" : "=&v"(r) : "v"(vb), "i"(OFF) : "memory"); return r;
; }
; template <int D0> __device__ __forceinline__ void pv_one(f32x16& od, int vb, bf16x8 pa0, bf16x8 pa1, bf16x8 pa2, bf16x8 pa3) {
;   const s16x4 l0 = tr_read<v_rd_off(D0, 0, 0)>(vb), h0 = tr_read<v_rd_off(D0, 0, 1)>(vb), l1 = tr_read<v_rd_off(D0, 1, 0)>(vb), h1 = tr_read<v_rd_off(D0, 1, 1)>(vb);
;   const s16x4 l2 = tr_read<v_rd_off(D0, 2, 0)>(vb), h2 = tr_read<v_rd_off(D0, 2, 1)>(vb), l3 = tr_read<v_rd_off(D0, 3, 0)>(vb), h3 = tr_read<v_rd_off(D0, 3, 1)>(vb);
;   asm volatile("s_waitcnt lgkmcnt(0)" ::: "memory"); SBAR();
;     ...
;   od = __builtin_amdgcn_mfma_f32_32x32x16_bf16(pa0, PK(l0, h0), od, 0, 0, 0);
;   od = __builtin_amdgcn_mfma_f32_32x32x16_bf16(pa1, PK(l1, h1), od, 0, 0, 0);
;   od = __builtin_amdgcn_mfma_f32_32x32x16_bf16(pa2, PK(l2, h2), od, 0, 0, 0);
	v_mfma_f32_32x32x16_bf16 v[80:95], v[240:243], v[232:235], v[80:95]
	ds_read_b128 v[240:243], v201 offset:49152
	v_addc_co_u32_e32 v129, vcc, -1, v169, vcc
	v_add_co_u32_e32 v130, vcc, s18, v168
	s_movk_i32 s18, 0xe000
	s_nop 0
	v_addc_co_u32_e32 v131, vcc, -1, v169, vcc
	global_load_dwordx4 v[140:143], v[128:129], off
	global_load_dwordx4 v[136:139], v[128:129], off offset:-256
	global_load_dwordx4 v[144:147], v[130:131], off
	v_mfma_f32_32x32x16_bf16 v[64:79], v[248:251], v[232:235], v[64:79]
	ds_read_b128 v[248:251], v181
	ds_read_b128 v[232:235], v187 offset:36864
	global_load_dwordx4 v[132:135], v[130:131], off offset:-256
	v_add_co_u32_e32 v128, vcc, s18, v166
	s_nop 1
	v_addc_co_u32_e32 v129, vcc, -1, v167, vcc
	global_load_dwordx4 v[128:131], v[128:129], off
	v_cvt_pk_bf16_f32 v158, v158, v159
	v_cvt_pk_bf16_f32 v159, v156, v157
	s_waitcnt lgkmcnt(1)
	v_mfma_f32_32x32x16_bf16 v[80:95], v[236:239], v[248:251], v[80:95]
	ds_read_b128 v[236:239], v189 offset:49152
	v_permlane32_swap_b32_e32 v211, v212
	v_cvt_pk_bf16_f32 v156, v162, v163
	v_cvt_pk_bf16_f32 v157, v160, v161
	v_cvt_pk_bf16_f32 v160, v154, v155
	v_cvt_pk_bf16_f32 v161, v152, v153
	v_cvt_pk_bf16_f32 v162, v150, v151
	v_mfma_f32_32x32x16_bf16 v[64:79], v[240:243], v[248:251], v[64:79]
	ds_read_b128 v[240:243], v179
	ds_read_b128 v[248:251], v188 offset:36864
	v_cvt_pk_bf16_f32 v163, v148, v149
	v_add_f32_e32 v211, v211, v212
	v_cvt_pk_bf16_f32 v148, v225, v228
	v_cvt_pk_bf16_f32 v149, v226, v229
	v_cvt_pk_bf16_f32 v150, v227, v230
	v_cvt_pk_bf16_f32 v151, v223, v224
	s_waitcnt lgkmcnt(1)
	v_mfma_f32_32x32x16_bf16 v[80:95], v[232:235], v[240:243], v[80:95]
	ds_read_b128 v[232:235], v190 offset:49152
	v_cvt_pk_bf16_f32 v152, v219, v221
	v_cvt_pk_bf16_f32 v153, v220, v222
	v_cvt_pk_bf16_f32 v154, v215, v217
	v_cvt_pk_bf16_f32 v155, v216, v218
	v_fma_f32 v176, v209, v176, v211
	v_mfma_f32_32x32x16_bf16 v[64:79], v[236:239], v[240:243], v[64:79]
	ds_read_b128 v[236:239], v177
	s_waitcnt lgkmcnt(0)
	v_mfma_f32_32x32x16_bf16 v[80:95], v[248:251], v[236:239], v[80:95]
	v_mfma_f32_32x32x16_bf16 v[64:79], v[232:235], v[236:239], v[64:79]
	s_lshl_b32 s31, s30, 14
	v_add_u32_e32 v180, s31, v178
	ds_read_b64_tr_b16 v[240:241], v180 offset:0
	ds_read_b64_tr_b16 v[242:243], v180 offset:2048
	ds_read_b64_tr_b16 v[248:249], v180 offset:512
	ds_read_b64_tr_b16 v[250:251], v180 offset:2560
	ds_read_b64_tr_b16 v[232:233], v180 offset:1024
	ds_read_b64_tr_b16 v[234:235], v180 offset:3072
	ds_read_b64_tr_b16 v[236:237], v180 offset:1536
	ds_read_b64_tr_b16 v[238:239], v180 offset:3584
	s_nop 3
	v_max3_f32 v194, v80, v81, v82
	v_max3_f32 v195, v64, v65, v66
	v_max3_f32 v194, v194, v83, v84
	v_max3_f32 v195, v195, v67, v68
	s_waitcnt lgkmcnt(4)
	v_mfma_f32_32x32x16_bf16 v[32:47], v[148:151], v[240:243], v[32:47]
	ds_read_b64_tr_b16 v[240:241], v180 offset:4096
	ds_read_b64_tr_b16 v[242:243], v180 offset:6144
	v_max3_f32 v194, v194, v85, v86
	v_max3_f32 v195, v195, v69, v70
	v_max3_f32 v194, v194, v87, v88
	v_max3_f32 v195, v195, v71, v72
	v_mfma_f32_32x32x16_bf16 v[48:63], v[148:151], v[248:251], v[48:63]
	ds_read_b64_tr_b16 v[248:249], v180 offset:4608
	ds_read_b64_tr_b16 v[250:251], v180 offset:6656
	v_max3_f32 v194, v194, v89, v90
	v_max3_f32 v195, v195, v73, v74
	v_max3_f32 v194, v194, v91, v92
	v_max3_f32 v195, v195, v75, v76
	s_waitcnt lgkmcnt(4)
	v_mfma_f32_32x32x16_bf16 v[16:31], v[148:151], v[232:235], v[16:31]
	ds_read_b64_tr_b16 v[232:233], v180 offset:5120
	ds_read_b64_tr_b16 v[234:235], v180 offset:7168
	v_max3_f32 v194, v194, v93, v94
	v_max3_f32 v195, v195, v77, v78
	v_max3_f32 v194, v194, v95, v195
	v_max_f32_e32 v194, v194, v79
	v_mfma_f32_32x32x16_bf16 v[0:15], v[148:151], v[236:239], v[0:15]
	ds_read_b64_tr_b16 v[236:237], v180 offset:5632
	ds_read_b64_tr_b16 v[238:239], v180 offset:7680
	v_mov_b32_e32 v195, v194
	s_nop 1
	v_permlane32_swap_b32_e32 v194, v195
	v_max_f32_e32 v194, v194, v195
	s_waitcnt lgkmcnt(4)
	v_mfma_f32_32x32x16_bf16 v[32:47], v[152:155], v[240:243], v[32:47]
	ds_read_b64_tr_b16 v[240:241], v180 offset:8192
	ds_read_b64_tr_b16 v[242:243], v180 offset:10240
	v_sub_f32_e32 v195, v194, v210
	v_cmp_ge_f32_e32 vcc, s15, v195
	v_mfma_f32_32x32x16_bf16 v[48:63], v[152:155], v[248:251], v[48:63]
	ds_read_b64_tr_b16 v[248:249], v180 offset:8704
	ds_read_b64_tr_b16 v[250:251], v180 offset:10752
	s_cmp_eq_u64 vcc, exec
	s_cselect_b64 s[40:41], -1, 0
	s_cbranch_scc1 .Lattn_fast1
	v_max_f32_e32 v194, v210, v194
	v_sub_f32_e32 v195, v210, v194
	v_mul_f32_e32 v195, 0x3dd53b94, v195
	v_exp_f32_e32 v214, v195
	v_mov_b32_e32 v210, v194
	s_branch .Lattn_join1

; #define SBAR() __builtin_amdgcn_sched_barrier(0)
; __device__ __forceinline__ void qkt(f32x16& p0, f32x16& p1, const char* Ks, const bf16x8* qr, const char* qrl, int r32, int hi) {
;   p0 = f32x16{}; p1 = f32x16{};
; #pragma unroll
;   for (int d0 = 0; d0 < 8; ++d0) { int cb = (d0 * 16 + hi * 8) * 2;
;     bf16x8 b0 = *reinterpret_cast<const bf16x8*>(Ks + KSWZ(r32, cb));
;     bf16x8 b1 = *reinterpret_cast<const bf16x8*>(Ks + KSWZ(32 + r32, cb));
;     p0 = __builtin_amdgcn_mfma_f32_32x32x16_bf16(b0, qr[d0], p0, 0, 0, 0);
;     p1 = __builtin_amdgcn_mfma_f32_32x32x16_bf16(b1, qr[d0], p1, 0, 0, 0); }
; #pragma unroll
;   for (int d0 = 8; d0 < 12; ++d0) { int cb = (d0 * 16 + hi * 8) * 2;
;     bf16x8 b0 = *reinterpret_cast<const bf16x8*>(Ks + KSWZ(r32, cb));
;     bf16x8 b1 = *reinterpret_cast<const bf16x8*>(Ks + KSWZ(32 + r32, cb));
;     bf16x8 qf = *reinterpret_cast<const bf16x8*>(qrl + (((2 * (d0 - 8) + hi) ^ ((r32 >> 1) & 7)) << 4));
;     p0 = __builtin_amdgcn_mfma_f32_32x32x16_bf16(b0, qf, p0, 0, 0, 0);
;     p1 = __builtin_amdgcn_mfma_f32_32x32x16_bf16(b1, qf, p1, 0, 0, 0); }
; }
; __device__ __forceinline__ void attn_unit(const bf16_t* __restrict__ Qb, const bf16_t* __restrict__ Kn, const bf16_t* __restrict__ Vh, const bf16_t* __restrict__ Kr,
;                                           bf16_t* GO, int seq, char* lds, const int tid) {
;     ...
;   { const int bp = bc == 0 ? 2 : bc - 1;
;     SBAR(); qkt(pB0, pB1, K_lds + bc * SHM_K, qr, qrl, r32, hi);
;     finishSM(pA0, pA1, alA, l_reg, pa0, pa1, pa2, pa3); SBAR();
.LBB0_1163:
	v_add_u32_e32 v199, 0xffff7000, v199
	v_add_u32_e32 v205, 0xffff7000, v205
	v_add_u32_e32 v206, 0xffff7000, v206
	v_add_u32_e32 v208, 0xffff7000, v208
	v_add_u32_e32 v207, 0xffff7000, v207
	v_add_u32_e32 v204, 0xffff7000, v204
	v_add_u32_e32 v203, 0xffff7000, v203
	v_add_u32_e32 v200, 0xffff7000, v200
	v_add_u32_e32 v191, 0xffff7000, v191
	v_add_u32_e32 v198, 0xffff7000, v198
	v_add_u32_e32 v187, 0xffff7000, v187
	v_add_u32_e32 v188, 0xffff7000, v188
	v_add_u32_e32 v202, 0xffff7000, v202
	v_add_u32_e32 v201, 0xffff7000, v201
	v_add_u32_e32 v189, 0xffff7000, v189
	v_add_u32_e32 v190, 0xffff7000, v190
	v_add_u32_e32 v185, 0xffff7000, v185
	v_add_u32_e32 v186, 0xffff7000, v186
	v_exp_f32_e32 v225, v225
	v_exp_f32_e32 v228, v228
	v_exp_f32_e32 v226, v226
	v_exp_f32_e32 v229, v229
	v_exp_f32_e32 v227, v227
	v_exp_f32_e32 v230, v230
	v_exp_f32_e32 v223, v223
	v_exp_f32_e32 v224, v224
	v_exp_f32_e32 v219, v219
	v_exp_f32_e32 v221, v221
	v_exp_f32_e32 v220, v220
	v_exp_f32_e32 v222, v222
	v_exp_f32_e32 v215, v215
	v_exp_f32_e32 v217, v217
	v_exp_f32_e32 v216, v216
	v_exp_f32_e32 v218, v218
	s_nop 0
	v_add_u32_e32 v68, s34, v199
	ds_read_b128 v[64:67], v68 offset:49152
	ds_read_b128 v[68:71], v68 offset:61440
	s_waitcnt vmcnt(0)
	v_add_u32_e32 v128, s34, v205
	s_waitcnt lgkmcnt(1)
	v_mfma_f32_32x32x16_bf16 v[80:95], v[64:67], v[124:127], 0
	s_waitcnt lgkmcnt(0)
	v_mfma_f32_32x32x16_bf16 v[64:79], v[68:71], v[124:127], 0
	ds_read_b128 v[124:127], v128 offset:49152
	ds_read_b128 v[128:131], v128 offset:61440
	s_waitcnt lgkmcnt(1)
	v_mfma_f32_32x32x16_bf16 v[80:95], v[124:127], v[120:123], v[80:95]
	v_add_u32_e32 v124, s34, v206
	s_waitcnt lgkmcnt(0)
	v_mfma_f32_32x32x16_bf16 v[64:79], v[128:131], v[120:123], v[64:79]
	ds_read_b128 v[120:123], v124 offset:49152
	ds_read_b128 v[124:127], v124 offset:61440
	s_waitcnt lgkmcnt(1)
	v_mfma_f32_32x32x16_bf16 v[80:95], v[120:123], v[116:119], v[80:95]
	v_add_u32_e32 v120, s34, v208
	s_waitcnt lgkmcnt(0)
	v_mfma_f32_32x32x16_bf16 v[64:79], v[124:127], v[116:119], v[64:79]
	ds_read_b128 v[116:119], v120 offset:49152
	ds_read_b128 v[120:123], v120 offset:61440
	s_waitcnt lgkmcnt(1)
	v_mfma_f32_32x32x16_bf16 v[80:95], v[116:119], v[112:115], v[80:95]
	v_add_u32_e32 v116, s34, v207
	s_waitcnt lgkmcnt(0)
	v_mfma_f32_32x32x16_bf16 v[64:79], v[120:123], v[112:115], v[64:79]
	ds_read_b128 v[112:115], v116 offset:49152
	ds_read_b128 v[116:119], v116 offset:61440
	v_exp_f32_e32 v120, v148
	v_exp_f32_e32 v121, v149
	s_waitcnt lgkmcnt(1)
	v_mfma_f32_32x32x16_bf16 v[80:95], v[112:115], v[108:111], v[80:95]
	v_add_u32_e32 v112, s34, v204
	s_waitcnt lgkmcnt(0)
	v_mfma_f32_32x32x16_bf16 v[64:79], v[116:119], v[108:111], v[64:79]
	ds_read_b128 v[108:111], v112 offset:49152
	ds_read_b128 v[112:115], v112 offset:61440
	v_exp_f32_e32 v116, v152
	v_exp_f32_e32 v117, v153
	v_exp_f32_e32 v118, v150
	v_exp_f32_e32 v119, v151
	s_waitcnt lgkmcnt(1)
	v_mfma_f32_32x32x16_bf16 v[80:95], v[108:111], v[104:107], v[80:95]
	v_add_u32_e32 v108, s34, v203
	s_waitcnt lgkmcnt(0)
	v_mfma_f32_32x32x16_bf16 v[64:79], v[112:115], v[104:107], v[64:79]
	ds_read_b128 v[104:107], v108 offset:49152
	ds_read_b128 v[108:111], v108 offset:61440
	v_exp_f32_e32 v112, v156
	v_exp_f32_e32 v113, v157
	v_exp_f32_e32 v114, v154
	v_exp_f32_e32 v115, v155
	s_waitcnt lgkmcnt(1)
	v_mfma_f32_32x32x16_bf16 v[80:95], v[104:107], v[100:103], v[80:95]
	v_add_u32_e32 v104, s34, v200
	s_waitcnt lgkmcnt(0)
	v_mfma_f32_32x32x16_bf16 v[64:79], v[108:111], v[100:103], v[64:79]
	ds_read_b128 v[100:103], v104 offset:49152
	ds_read_b128 v[104:107], v104 offset:61440
	v_exp_f32_e32 v108, v160
	v_exp_f32_e32 v109, v161
	v_exp_f32_e32 v110, v158
	v_exp_f32_e32 v111, v159
	s_waitcnt lgkmcnt(1)
	v_mfma_f32_32x32x16_bf16 v[80:95], v[100:103], v[96:99], v[80:95]
	v_add_u32_e32 v100, s34, v202
	s_waitcnt lgkmcnt(0)
	v_mfma_f32_32x32x16_bf16 v[64:79], v[104:107], v[96:99], v[64:79]
	v_add_u32_e32 v96, s34, v191
	ds_read_b128 v[96:99], v96 offset:49152
	ds_read_b128 v[100:103], v100 offset:61440
	ds_read_b128 v[104:107], v182
	s_waitcnt lgkmcnt(0)
	v_mfma_f32_32x32x16_bf16 v[80:95], v[96:99], v[104:107], v[80:95]
	v_add_u32_e32 v96, s34, v198
	ds_read_b128 v[96:99], v96 offset:49152
	v_mfma_f32_32x32x16_bf16 v[64:79], v[100:103], v[104:107], v[64:79]
	v_add_u32_e32 v100, s34, v201
	ds_read_b128 v[100:103], v100 offset:61440
	ds_read_b128 v[104:107], v181
	s_waitcnt lgkmcnt(0)
	v_mfma_f32_32x32x16_bf16 v[80:95], v[96:99], v[104:107], v[80:95]
	v_add_u32_e32 v96, s34, v187
	ds_read_b128 v[96:99], v96 offset:49152
	v_mfma_f32_32x32x16_bf16 v[64:79], v[100:103], v[104:107], v[64:79]
	v_add_u32_e32 v100, s34, v189
	ds_read_b128 v[100:103], v100 offset:61440
	ds_read_b128 v[104:107], v179
	s_waitcnt lgkmcnt(0)
	v_mfma_f32_32x32x16_bf16 v[80:95], v[96:99], v[104:107], v[80:95]
	v_add_u32_e32 v96, s34, v188
	ds_read_b128 v[96:99], v96 offset:49152
	v_mfma_f32_32x32x16_bf16 v[64:79], v[100:103], v[104:107], v[64:79]
	v_add_u32_e32 v100, s34, v190
	ds_read_b128 v[100:103], v100 offset:61440
	ds_read_b128 v[104:107], v177
	s_waitcnt lgkmcnt(0)
; #define SBAR() __builtin_amdgcn_sched_barrier(0)
; __device__ __forceinline__ void finishSM(f32x16& p0, f32x16& p1, float alpha, float& l_reg, bf16x8& pa0, bf16x8& pa1, bf16x8& pa2, bf16x8& pa3) {
; #pragma unroll
;   for (int r = 0; r < 16; ++r) p1[r] = __builtin_amdgcn_exp2f(p1[r]);
;   float ps = 0;
; #pragma unroll
;   for (int r = 0; r < 16; ++r) ps += p0[r];
; #pragma unroll
;   for (int r = 0; r < 16; ++r) ps += p1[r];
;   { auto rr = __builtin_amdgcn_permlane32_swap(__float_as_uint(ps), __float_as_uint(ps), false, false);
;     ps = __uint_as_float(rr[0]) + __uint_as_float(rr[1]); }
;   l_reg = l_reg * alpha + ps;
;     ...
;   PK4(p0, 0, pa0); PK4(p0, 8, pa1); PK4(p1, 0, pa2); PK4(p1, 8, pa3);
;     ...
; }
; template <int D0> __device__ __forceinline__ void pv_one(f32x16& od, int vb, bf16x8 pa0, bf16x8 pa1, bf16x8 pa2, bf16x8 pa3) {
;   const s16x4 l0 = tr_read<v_rd_off(D0, 0, 0)>(vb), h0 = tr_read<v_rd_off(D0, 0, 1)>(vb), l1 = tr_read<v_rd_off(D0, 1, 0)>(vb), h1 = tr_read<v_rd_off(D0, 1, 1)>(vb);
;   const s16x4 l2 = tr_read<v_rd_off(D0, 2, 0)>(vb), h2 = tr_read<v_rd_off(D0, 2, 1)>(vb), l3 = tr_read<v_rd_off(D0, 3, 0)>(vb), h3 = tr_read<v_rd_off(D0, 3, 1)>(vb);
;   asm volatile("s_waitcnt lgkmcnt(0)" ::: "memory"); SBAR();
;     ...
;   od = __builtin_amdgcn_mfma_f32_32x32x16_bf16(pa0, PK(l0, h0), od, 0, 0, 0);
;   od = __builtin_amdgcn_mfma_f32_32x32x16_bf16(pa1, PK(l1, h1), od, 0, 0, 0);
;   od = __builtin_amdgcn_mfma_f32_32x32x16_bf16(pa2, PK(l2, h2), od, 0, 0, 0);
;   od = __builtin_amdgcn_mfma_f32_32x32x16_bf16(pa3, PK(l3, h3), od, 0, 0, 0);
;     ...
; }
; __device__ __forceinline__ void pv_d0(f32x16* o, int vb, bf16x8 pa0, bf16x8 pa1, bf16x8 pa2, bf16x8 pa3) {
;   pv_one<0>(o[0], vb, pa0, pa1, pa2, pa3); pv_one<1>(o[1], vb, pa0, pa1, pa2, pa3); pv_one<2>(o[2], vb, pa0, pa1, pa2, pa3); pv_one<3>(o[3], vb, pa0, pa1, pa2, pa3);
	v_mfma_f32_32x32x16_bf16 v[80:95], v[96:99], v[104:107], v[80:95]
	v_add_f32_e32 v96, 0, v225
	v_add_f32_e32 v96, v228, v96
	v_add_f32_e32 v96, v226, v96
	v_add_f32_e32 v96, v229, v96
	v_add_f32_e32 v96, v227, v96
	v_add_f32_e32 v96, v230, v96
	v_add_f32_e32 v96, v223, v96
	v_add_f32_e32 v96, v224, v96
	v_add_f32_e32 v96, v219, v96
	v_add_f32_e32 v96, v221, v96
	v_add_f32_e32 v96, v220, v96
	v_add_f32_e32 v96, v222, v96
	v_mfma_f32_32x32x16_bf16 v[64:79], v[100:103], v[104:107], v[64:79]
	v_exp_f32_e32 v106, v162
	v_add_f32_e32 v96, v215, v96
	v_exp_f32_e32 v107, v163
	v_add_f32_e32 v96, v217, v96
	v_add_f32_e32 v96, v216, v96
	v_add_f32_e32 v96, v218, v96
	v_add_f32_e32 v96, v106, v96
	v_add_f32_e32 v96, v107, v96
	v_add_f32_e32 v96, v108, v96
	v_add_f32_e32 v96, v109, v96
	v_add_f32_e32 v96, v110, v96
	v_add_f32_e32 v96, v111, v96
	v_add_f32_e32 v96, v112, v96
	v_add_f32_e32 v96, v113, v96
	v_add_f32_e32 v96, v114, v96
	v_add_f32_e32 v96, v115, v96
	v_add_f32_e32 v96, v116, v96
	v_add_f32_e32 v96, v117, v96
	v_add_f32_e32 v96, v118, v96
	v_add_f32_e32 v96, v119, v96
	v_add_f32_e32 v96, v120, v96
	v_add_f32_e32 v100, v121, v96
	v_mov_b32_e32 v101, v100
	v_cvt_pk_bf16_f32 v96, v225, v228
	v_cvt_pk_bf16_f32 v97, v226, v229
	v_cvt_pk_bf16_f32 v98, v227, v230
	v_cvt_pk_bf16_f32 v99, v223, v224
	s_nop 1
	v_permlane32_swap_b32_e32 v100, v101
	v_cvt_pk_bf16_f32 v102, v219, v221
	v_cvt_pk_bf16_f32 v103, v220, v222
	v_cvt_pk_bf16_f32 v104, v215, v217
	v_cvt_pk_bf16_f32 v105, v216, v218
	v_cvt_pk_bf16_f32 v106, v106, v107
	v_cvt_pk_bf16_f32 v107, v108, v109
	v_cvt_pk_bf16_f32 v108, v110, v111
	v_cvt_pk_bf16_f32 v109, v112, v113
	v_cvt_pk_bf16_f32 v110, v114, v115
	v_cvt_pk_bf16_f32 v111, v116, v117
	v_cvt_pk_bf16_f32 v112, v118, v119
	v_cvt_pk_bf16_f32 v113, v120, v121
	s_nop 0
	s_addk_i32 s31, 0xc000
	s_cmp_lg_u32 s30, 0
	s_cselect_b32 s18, s31, 0x8000
	v_add_u32_e32 v130, s18, v178
	ds_read_b64_tr_b16 v[114:115], v130 offset:0
	ds_read_b64_tr_b16 v[116:117], v130 offset:0x800
	ds_read_b64_tr_b16 v[118:119], v130 offset:0x1000
	ds_read_b64_tr_b16 v[120:121], v130 offset:0x1800
	ds_read_b64_tr_b16 v[122:123], v130 offset:0x2000
	ds_read_b64_tr_b16 v[124:125], v130 offset:0x2800
	ds_read_b64_tr_b16 v[126:127], v130 offset:0x3000
	ds_read_b64_tr_b16 v[128:129], v130 offset:0x3800
	s_waitcnt lgkmcnt(0)
	s_nop 0
	v_mfma_f32_32x32x16_bf16 v[32:47], v[96:99], v[114:117], v[32:47]
	ds_read_b64_tr_b16 v[114:115], v130 offset:0x200
	ds_read_b64_tr_b16 v[116:117], v130 offset:0xa00
	v_mfma_f32_32x32x16_bf16 v[32:47], v[102:105], v[118:121], v[32:47]
	ds_read_b64_tr_b16 v[118:119], v130 offset:0x1200
	ds_read_b64_tr_b16 v[120:121], v130 offset:0x1a00
	v_mfma_f32_32x32x16_bf16 v[32:47], v[106:109], v[122:125], v[32:47]
	ds_read_b64_tr_b16 v[122:123], v130 offset:0x2200
	ds_read_b64_tr_b16 v[124:125], v130 offset:0x2a00
	v_mfma_f32_32x32x16_bf16 v[32:47], v[110:113], v[126:129], v[32:47]
	ds_read_b64_tr_b16 v[126:127], v130 offset:0x3200
	ds_read_b64_tr_b16 v[128:129], v130 offset:0x3a00
	s_waitcnt lgkmcnt(0)
	v_mfma_f32_32x32x16_bf16 v[48:63], v[96:99], v[114:117], v[48:63]
	ds_read_b64_tr_b16 v[114:115], v130 offset:0x400
	ds_read_b64_tr_b16 v[116:117], v130 offset:0xc00
	v_mfma_f32_32x32x16_bf16 v[48:63], v[102:105], v[118:121], v[48:63]
	ds_read_b64_tr_b16 v[118:119], v130 offset:0x1400
	ds_read_b64_tr_b16 v[120:121], v130 offset:0x1c00
	v_mfma_f32_32x32x16_bf16 v[48:63], v[106:109], v[122:125], v[48:63]
	ds_read_b64_tr_b16 v[122:123], v130 offset:0x2400
	ds_read_b64_tr_b16 v[124:125], v130 offset:0x2c00
	v_mfma_f32_32x32x16_bf16 v[48:63], v[110:113], v[126:129], v[48:63]
	ds_read_b64_tr_b16 v[126:127], v130 offset:0x3400
	ds_read_b64_tr_b16 v[128:129], v130 offset:0x3c00
	s_waitcnt lgkmcnt(0)
	v_mfma_f32_32x32x16_bf16 v[16:31], v[96:99], v[114:117], v[16:31]
	ds_read_b64_tr_b16 v[114:115], v130 offset:0x600
	ds_read_b64_tr_b16 v[116:117], v130 offset:0xe00
	v_mfma_f32_32x32x16_bf16 v[16:31], v[102:105], v[118:121], v[16:31]
	ds_read_b64_tr_b16 v[118:119], v130 offset:0x1600
	ds_read_b64_tr_b16 v[120:121], v130 offset:0x1e00
	v_mfma_f32_32x32x16_bf16 v[16:31], v[106:109], v[122:125], v[16:31]
	ds_read_b64_tr_b16 v[122:123], v130 offset:0x2600
	ds_read_b64_tr_b16 v[124:125], v130 offset:0x2e00
	v_mfma_f32_32x32x16_bf16 v[16:31], v[110:113], v[126:129], v[16:31]
	ds_read_b64_tr_b16 v[126:127], v130 offset:0x3600
	ds_read_b64_tr_b16 v[128:129], v130 offset:0x3e00
	s_waitcnt lgkmcnt(0)
	v_mfma_f32_32x32x16_bf16 v[0:15], v[96:99], v[114:117], v[0:15]
	v_max_f32_e32 v96, v81, v81
	v_max_f32_e32 v97, v80, v80
	v_max_f32_e32 v96, v97, v96
	v_max3_f32 v96, v96, v82, v83
	v_max3_f32 v96, v96, v84, v85
	v_max3_f32 v96, v96, v86, v87
	v_max3_f32 v96, v96, v88, v89
	v_max3_f32 v96, v96, v90, v91
	v_max3_f32 v96, v96, v92, v93
	v_mfma_f32_32x32x16_bf16 v[0:15], v[102:105], v[118:121], v[0:15]
	v_max3_f32 v96, v96, v94, v95
	v_max3_f32 v96, v96, v64, v65
	v_max3_f32 v96, v96, v66, v67
	v_max3_f32 v96, v96, v68, v69
	v_max3_f32 v96, v96, v70, v71
	v_max3_f32 v96, v96, v72, v73
	v_max3_f32 v96, v96, v74, v75
	v_max3_f32 v96, v96, v76, v77
	v_mfma_f32_32x32x16_bf16 v[0:15], v[106:109], v[122:125], v[0:15]
	v_max3_f32 v96, v96, v78, v79
	v_mov_b32_e32 v97, v96
	s_nop 1
	v_permlane32_swap_b32_e32 v96, v97
	v_max_f32_e32 v97, v97, v97
	v_max_f32_e32 v96, v96, v96
	v_max_f32_e32 v96, v96, v97
	v_sub_f32_e32 v97, v96, v210
	v_cmp_ge_f32_e32 vcc, s15, v97
	v_max_f32_e32 v97, v210, v210
	v_max_f32_e32 v97, v97, v96
	v_mfma_f32_32x32x16_bf16 v[0:15], v[110:113], v[126:129], v[0:15]
	v_sub_f32_e32 v96, v210, v97
	v_mul_f32_e32 v96, 0x3dd53b94, v96
	v_exp_f32_e32 v96, v96
	s_cmp_eq_u64 vcc, exec
	s_cselect_b64 s[40:41], -1, 0
	v_cndmask_b32_e64 v96, v96, 1.0, s[40:41]
	v_cmp_gt_f32_e32 vcc, 1.0, v96
	s_cbranch_vccz .LBB0_1167
	s_and_saveexec_b64 s[18:19], s[38:39]
	ds_write_b32 v175, v96 offset:128
	s_or_b64 exec, exec, s[18:19]
	s_waitcnt lgkmcnt(0)
	v_add_u32_e32 v98, v173, v164
	ds_read_b128 v[102:105], v98 offset:224
	ds_read_b128 v[106:109], v98 offset:192
	ds_read_b128 v[110:113], v98 offset:160
	ds_read_b128 v[114:117], v98 offset:128
	s_waitcnt lgkmcnt(3)
	v_pk_mul_f32 v[44:45], v[44:45], v[102:103]
	s_waitcnt lgkmcnt(2)
	v_pk_mul_f32 v[40:41], v[40:41], v[106:107]
	s_waitcnt lgkmcnt(1)
	v_pk_mul_f32 v[36:37], v[36:37], v[110:111]
	v_pk_mul_f32 v[46:47], v[46:47], v[104:105]
	v_pk_mul_f32 v[42:43], v[42:43], v[108:109]
	v_pk_mul_f32 v[38:39], v[38:39], v[112:113]
	s_waitcnt lgkmcnt(0)
	v_pk_mul_f32 v[34:35], v[34:35], v[116:117]
	v_pk_mul_f32 v[32:33], v[32:33], v[114:115]
	v_pk_mul_f32 v[60:61], v[60:61], v[102:103]
	v_pk_mul_f32 v[56:57], v[56:57], v[106:107]
	v_pk_mul_f32 v[52:53], v[52:53], v[110:111]
	v_pk_mul_f32 v[62:63], v[62:63], v[104:105]
	v_pk_mul_f32 v[58:59], v[58:59], v[108:109]
	v_pk_mul_f32 v[54:55], v[54:55], v[112:113]
	v_pk_mul_f32 v[50:51], v[50:51], v[116:117]
	v_pk_mul_f32 v[48:49], v[48:49], v[114:115]
	v_pk_mul_f32 v[28:29], v[28:29], v[102:103]
	v_pk_mul_f32 v[24:25], v[24:25], v[106:107]
	v_pk_mul_f32 v[20:21], v[20:21], v[110:111]
	v_pk_mul_f32 v[30:31], v[30:31], v[104:105]
	v_pk_mul_f32 v[26:27], v[26:27], v[108:109]
	v_pk_mul_f32 v[22:23], v[22:23], v[112:113]
	v_pk_mul_f32 v[18:19], v[18:19], v[116:117]
	v_pk_mul_f32 v[16:17], v[16:17], v[114:115]
	v_pk_mul_f32 v[12:13], v[12:13], v[102:103]
	v_pk_mul_f32 v[8:9], v[8:9], v[106:107]
	v_pk_mul_f32 v[4:5], v[4:5], v[110:111]
	v_pk_mul_f32 v[14:15], v[14:15], v[104:105]
	v_pk_mul_f32 v[10:11], v[10:11], v[108:109]
	v_pk_mul_f32 v[6:7], v[6:7], v[112:113]
	v_pk_mul_f32 v[2:3], v[2:3], v[116:117]
	v_pk_mul_f32 v[0:1], v[0:1], v[114:115]
